# v56 + static priority raise for the younger wave half in attention (group B base prio 1, MFMA blocks prio 2)
# speedup vs baseline: 1.0056x; 1.0004x over previous
; #define LAS __attribute__((address_space(3)))
; template <bool MLA, bool grpB>
; __device__ __forceinline__ void attn_unit_g(LAS unsigned char* lds, const AttnPtrs& P, int b, int h, int qblk) {
;     ...
;     auto qk = [&](int koff) {
;         if (MLA) {
;         } else {
; #pragma unroll
;             for (int blk = 0; blk < 2; ++blk)
; #pragma unroll
;                 for (int g = 0; g < 4; ++g) { const f32x4 c4 = *(const LAS f32x4*)(lds + koff + KTILE + (32 * blk + 16 * hi + 4 * g) * 4);
; #pragma unroll
;                     for (int e = 0; e < 4; ++e) sc[blk][4 * g + e] = c4[e]; }
;         }
;         const LAS unsigned char* ka = lds + koff + karow;
;         bf16x8 a[PFD];
;         auto ld = [&](int i) -> bf16x8 {
;             const int d0 = i >> 1, blk = i & 1, seg = 2 * d0;
;             int so;
;             if (MLA) so = (((seg + hi) & 24) | (((seg + hi) ^ kswz) & 7)) * 16; else so = ((seg + hi) ^ kswz) * 16;
;             return *(const LAS bf16x8*)(ka + blk * 32 * KROW + so);
;         };
; #pragma unroll
;         for (int i = 0; i < PFD; ++i) a[i] = ld(i);
; #pragma unroll
;         for (int i = 0; i < 2 * ND0; ++i) {
;             const f32x16 zc = {0.f, 0.f, 0.f, 0.f, 0.f, 0.f, 0.f, 0.f, 0.f, 0.f, 0.f, 0.f, 0.f, 0.f, 0.f, 0.f};
;             sc[i & 1] = __builtin_amdgcn_mfma_f32_32x32x16_bf16(a[i % PFD], qf[i >> 1], (MLA && i < 2) ? zc : sc[i & 1], 0, 0, 0);
;             if (i + PFD < 2 * ND0) a[i % PFD] = ld(i + PFD);
;         }
;         __builtin_amdgcn_sched_group_barrier(0x100, PFD, 0);
; #pragma unroll
;         for (int i = 0; i < 2 * ND0; ++i) { __builtin_amdgcn_sched_group_barrier(0x008, 1, 0); __builtin_amdgcn_sched_group_barrier(0x100, 1, 0); }
;         __builtin_amdgcn_sched_barrier(0);
;     };
;     ...
;     dma_k(jl, 0); dma_v(jl, 0); dma_k(jl - 1, KSLOT);
;     dma_k(jl - 2, 2 * KSLOT); dma_v(jl - 1, VTILE);
;     if (MLA) asm volatile("s_waitcnt vmcnt(5)\n\ts_barrier" ::: "memory"); else asm volatile("s_waitcnt vmcnt(4)\n\ts_barrier" ::: "memory");
;     if (grpB) qk(0);
.LBB0_1140:
	v_and_b32_e32 v2, 3, v4
	v_lshrrev_b32_e32 v39, 1, v4
	v_lshlrev_b32_e32 v0, 2, v34
	v_and_or_b32 v2, v39, 12, v2
	s_lshl_b64 s[12:13], s[36:37], 7
	v_and_or_b32 v0, v0, 16, v2
	v_bfe_u32 v5, v2, 1, 2
	v_and_b32_e32 v48, 4, v4
	v_lshl_add_u64 v[2:3], v[154:155], 0, s[12:13]
	s_add_i32 m0, s63, 0x1c400
	v_mad_u32_u24 v161, v0, s69, 0
	global_load_lds_dwordx4 v[2:3], off
	v_lshl_add_u64 v[2:3], v[156:157], 0, s[12:13]
	s_add_i32 m0, s63, 0x1e400
	v_bitop3_b32 v0, v5, v159, v48 bitop3:0x36
	global_load_lds_dwordx4 v[2:3], off
	v_lshlrev_b32_e32 v162, 4, v0
	s_waitcnt vmcnt(5)
	s_barrier
	v_add_u32_e32 v0, v161, v162
	ds_read_b128 v[10:13], v0
	ds_read_b128 v[6:9], v0 offset:12288
	v_or_b32_e32 v2, 2, v159
	v_or_b32_e32 v3, 4, v159
	v_bitop3_b32 v2, v5, v2, v48 bitop3:0x36
	v_bitop3_b32 v3, v5, v3, v48 bitop3:0x36
	v_lshlrev_b32_e32 v163, 4, v2
	v_lshlrev_b32_e32 v164, 4, v3
	v_add_u32_e32 v2, v161, v163
	v_add_u32_e32 v3, v161, v164
	ds_read_b128 v[14:17], v2
	ds_read_b128 v[40:43], v2 offset:12288
	ds_read_b128 v[44:47], v3
	ds_read_b128 v[66:69], v3 offset:12288
	s_waitcnt vmcnt(0) lgkmcnt(0)
	v_mfma_f32_32x32x16_bf16 v[18:33], v[10:13], v[98:101], 0
	v_or_b32_e32 v10, 6, v159
	v_bitop3_b32 v5, v5, v10, v48 bitop3:0x36
	v_lshlrev_b32_e32 v165, 4, v5
	v_add_u32_e32 v5, v161, v165
	ds_read_b128 v[10:13], v5
	s_mov_b32 s12, 0
	s_mov_b32 s13, s12
	v_mfma_f32_32x32x16_bf16 v[50:65], v[6:9], v[98:101], 0
	ds_read_b128 v[6:9], v5 offset:12288
	s_ashr_i32 s40, s16, 6
	v_bfe_u32 v48, v4, 1, 3
	s_mov_b32 s14, s12
	s_mov_b32 s15, s12
	s_mov_b32 s16, s12
	s_mov_b32 s17, s12
	v_mfma_f32_32x32x16_bf16 v[18:33], v[14:17], v[102:105], v[18:33]
	ds_read_b128 v[14:17], v0 offset:128
	s_mov_b32 s18, s12
	s_mov_b32 s19, s12
	s_mov_b32 s20, s12
	s_mov_b32 s21, s12
	s_mov_b32 s22, s12
	s_mov_b32 s23, s12
	v_mfma_f32_32x32x16_bf16 v[50:65], v[40:43], v[102:105], v[50:65]
	ds_read_b128 v[40:43], v0 offset:12416
	s_mov_b32 s24, s12
	s_mov_b32 s25, s12
	s_mov_b32 s26, s12
	s_mov_b32 s27, s12
	s_setprio 2
	v_mfma_f32_32x32x16_bf16 v[18:33], v[44:47], v[106:109], v[18:33]
	ds_read_b128 v[44:47], v2 offset:128
	v_mfma_f32_32x32x16_bf16 v[50:65], v[66:69], v[106:109], v[50:65]
	ds_read_b128 v[66:69], v2 offset:12416
	s_waitcnt lgkmcnt(5)
	v_mfma_f32_32x32x16_bf16 v[18:33], v[10:13], v[110:113], v[18:33]
	ds_read_b128 v[10:13], v3 offset:128
	s_waitcnt lgkmcnt(5)
	v_mfma_f32_32x32x16_bf16 v[50:65], v[6:9], v[110:113], v[50:65]
	ds_read_b128 v[6:9], v3 offset:12416
	s_waitcnt lgkmcnt(5)
	v_mfma_f32_32x32x16_bf16 v[18:33], v[14:17], v[114:117], v[18:33]
	ds_read_b128 v[14:17], v5 offset:128
	s_waitcnt lgkmcnt(5)
	v_mfma_f32_32x32x16_bf16 v[50:65], v[40:43], v[114:117], v[50:65]
	ds_read_b128 v[40:43], v5 offset:12416
	s_waitcnt lgkmcnt(5)
	v_mfma_f32_32x32x16_bf16 v[18:33], v[44:47], v[118:121], v[18:33]
	ds_read_b128 v[44:47], v0 offset:256
	s_waitcnt lgkmcnt(5)
	v_mfma_f32_32x32x16_bf16 v[50:65], v[66:69], v[118:121], v[50:65]
	ds_read_b128 v[66:69], v0 offset:12544
	s_waitcnt lgkmcnt(5)
	v_mfma_f32_32x32x16_bf16 v[18:33], v[10:13], v[122:125], v[18:33]
	ds_read_b128 v[10:13], v2 offset:256
	s_waitcnt lgkmcnt(5)
	v_mfma_f32_32x32x16_bf16 v[50:65], v[6:9], v[122:125], v[50:65]
	ds_read_b128 v[6:9], v2 offset:12544
	s_waitcnt lgkmcnt(5)
	v_mfma_f32_32x32x16_bf16 v[18:33], v[14:17], v[126:129], v[18:33]
	ds_read_b128 v[14:17], v3 offset:256
	s_waitcnt lgkmcnt(5)
	v_mfma_f32_32x32x16_bf16 v[50:65], v[40:43], v[126:129], v[50:65]
	ds_read_b128 v[40:43], v3 offset:12544
	s_waitcnt lgkmcnt(5)
	v_mfma_f32_32x32x16_bf16 v[18:33], v[44:47], v[130:133], v[18:33]
	ds_read_b128 v[44:47], v5 offset:256
	s_waitcnt lgkmcnt(5)
	v_mfma_f32_32x32x16_bf16 v[50:65], v[66:69], v[130:133], v[50:65]
	ds_read_b128 v[66:69], v5 offset:12544
	s_waitcnt lgkmcnt(5)
	v_mfma_f32_32x32x16_bf16 v[18:33], v[10:13], v[134:137], v[18:33]
	s_waitcnt lgkmcnt(4)
	v_mfma_f32_32x32x16_bf16 v[50:65], v[6:9], v[134:137], v[50:65]
	s_waitcnt lgkmcnt(3)
	v_mfma_f32_32x32x16_bf16 v[18:33], v[14:17], v[138:141], v[18:33]
	s_setprio 1
	v_mov_b64_e32 v[2:3], s[12:13]
	v_mov_b64_e32 v[4:5], s[14:15]
	v_mov_b64_e32 v[6:7], s[16:17]
	v_mov_b64_e32 v[8:9], s[18:19]
	v_mov_b64_e32 v[10:11], s[20:21]
	v_mov_b64_e32 v[12:13], s[22:23]
	v_mov_b64_e32 v[14:15], s[24:25]
	s_waitcnt lgkmcnt(2)
	v_mfma_f32_32x32x16_bf16 v[50:65], v[40:43], v[138:141], v[50:65]
	v_mov_b64_e32 v[16:17], s[26:27]
	s_waitcnt lgkmcnt(1)
	v_mfma_f32_32x32x16_bf16 v[18:33], v[44:47], v[142:145], v[18:33]
	s_waitcnt lgkmcnt(0)
	v_mfma_f32_32x32x16_bf16 v[50:65], v[66:69], v[142:145], v[50:65]
	v_lshl_add_u32 v34, v34, 7, 0
	v_add_u32_e32 v167, 0x18400, v34
	v_lshlrev_b32_e32 v34, 1, v159
	v_cmp_eq_u32_e32 vcc, 0, v35
	v_bitop3_b32 v35, v34, v39, 7 bitop3:0x78
	v_lshlrev_b32_e32 v168, 4, v35
	v_bitop3_b32 v35, v34, v48, 1 bitop3:0x36
	v_cndmask_b32_e64 v0, 13, 17, vcc
	v_cmp_eq_u32_e32 vcc, 0, v36
	v_lshlrev_b32_e32 v169, 4, v35
	v_bitop3_b32 v35, v34, v48, 4 bitop3:0x36
	v_bitop3_b32 v34, v34, v48, 5 bitop3:0x36
	v_cndmask_b32_e64 v158, 13, 17, vcc
	s_lshl_b32 s14, s41, 10
	v_cmp_eq_u32_e32 vcc, 0, v38
	v_add_u32_e32 v166, 0, v37
	v_lshlrev_b32_e32 v175, 4, v35
	v_lshlrev_b32_e32 v177, 4, v34
	v_mov_b64_e32 v[48:49], v[16:17]
	v_mov_b64_e32 v[80:81], v[16:17]
	v_mov_b64_e32 v[96:97], v[16:17]
	s_add_i32 s13, s40, 1
	s_add_i32 s18, s14, 0
	v_cndmask_b32_e64 v160, 13, 17, vcc
	v_mov_b32_e32 v178, 0xf149f2ca
	s_movk_i32 s19, 0x6100
	s_mov_b32 s20, 0xc200
	s_mov_b32 s15, 0x12300
	s_movk_i32 s21, 0x4000
	s_mov_b32 s14, 0x8000
	v_mov_b32_e32 v176, 0
	s_mov_b32 s36, s71
	v_mov_b64_e32 v[46:47], v[14:15]
	v_mov_b64_e32 v[44:45], v[12:13]
	v_mov_b64_e32 v[42:43], v[10:11]
	v_mov_b64_e32 v[40:41], v[8:9]
	v_mov_b64_e32 v[38:39], v[6:7]
	v_mov_b64_e32 v[36:37], v[4:5]
	v_mov_b64_e32 v[34:35], v[2:3]
	v_mov_b64_e32 v[78:79], v[14:15]
	v_mov_b64_e32 v[76:77], v[12:13]
	v_mov_b64_e32 v[74:75], v[10:11]
	v_mov_b64_e32 v[72:73], v[8:9]
	v_mov_b64_e32 v[70:71], v[6:7]
	v_mov_b64_e32 v[68:69], v[4:5]
	v_mov_b64_e32 v[66:67], v[2:3]
	v_mov_b64_e32 v[94:95], v[14:15]
	v_mov_b64_e32 v[92:93], v[12:13]
	v_mov_b64_e32 v[90:91], v[10:11]
	v_mov_b64_e32 v[88:89], v[8:9]
	v_mov_b64_e32 v[86:87], v[6:7]
	v_mov_b64_e32 v[84:85], v[4:5]
	v_mov_b64_e32 v[82:83], v[2:3]

; __device__ __forceinline__ unsigned cvt_pk_bf16(float lo, float hi) { unsigned r; asm volatile("v_cvt_pk_bf16_f32 %0, %1, %2" : "=v"(r) : "v"(lo), "v"(hi)); return r; }
; #define LAS __attribute__((address_space(3)))
; template <bool MLA, bool grpB>
; __device__ __forceinline__ void attn_unit_g(LAS unsigned char* lds, const AttnPtrs& P, int b, int h, int qblk) {
;     ...
;         float ps = 0.f;
; #pragma unroll
;         for (int blk = 0; blk < 2; ++blk)
; #pragma unroll
;             for (int r = 0; r < 16; ++r) { const float pv_ = __builtin_amdgcn_exp2f(sc[blk][r] - mref); sc[blk][r] = pv_; ps += pv_; }
;         lrun += ps;
; #pragma unroll
;         for (int blk = 0; blk < 2; ++blk)
; #pragma unroll
;             for (int ks = 0; ks < 2; ++ks) { u32x4 w;
;                 w.x = pg8::cvt_pk_bf16(sc[blk][8 * ks + 0], sc[blk][8 * ks + 1]); w.y = pg8::cvt_pk_bf16(sc[blk][8 * ks + 2], sc[blk][8 * ks + 3]);
;                 w.z = pg8::cvt_pk_bf16(sc[blk][8 * ks + 4], sc[blk][8 * ks + 5]); w.w = pg8::cvt_pk_bf16(sc[blk][8 * ks + 6], sc[blk][8 * ks + 7]);
;                 pb[blk][ks] = __builtin_bit_cast(bf16x8, w); }
;         __builtin_amdgcn_sched_barrier(0);
;     };
;     auto pv = [&](int voff) {
;         const LAS unsigned char* va = lds + varow + voff;
;         bf16x8 a[PFD];
;         auto ld = [&](int i) -> bf16x8 {
;             const int dvb = i & 3, bk = i >> 2, so = ((4 * (bk >> 1) + 2 * hi + (bk & 1)) ^ vswz) * 16;
;             return *(const LAS bf16x8*)(va + 32 * dvb * VROW + so);
;         };
; #pragma unroll
;         for (int i = 0; i < PFD; ++i) a[i] = ld(i);
; #pragma unroll
;         for (int i = 0; i < 16; ++i) {
;             o[i & 3] = __builtin_amdgcn_mfma_f32_32x32x16_bf16(a[i % PFD], pb[i >> 3][(i >> 2) & 1], o[i & 3], 0, 0, 0);
;             if (i + PFD < 16) a[i % PFD] = ld(i + PFD);
;         }
;         __builtin_amdgcn_sched_group_barrier(0x100, PFD, 0);
; #pragma unroll
;         for (int i = 0; i < 16; ++i) { __builtin_amdgcn_sched_group_barrier(0x008, 1, 0); __builtin_amdgcn_sched_group_barrier(0x100, 1, 0); }
;         __builtin_amdgcn_sched_barrier(0);
.LBB0_1151:
	v_add_u32_e32 v246, s12, v167
	v_add_u32_e32 v210, v246, v168
	ds_read_b128 v[196:199], v210
	ds_read_b128 v[202:205], v210 offset:4096
	ds_read_b128 v[206:209], v210 offset:8192
	ds_read_b128 v[210:213], v210 offset:12288
	v_add_u32_e32 v222, v246, v169
	ds_read_b128 v[214:217], v222
	ds_read_b128 v[218:221], v222 offset:4096
	v_sub_f32_e32 v18, v18, v178
	v_exp_f32_e32 v18, v18
	v_sub_f32_e32 v19, v19, v178
	v_exp_f32_e32 v19, v19
	v_sub_f32_e32 v20, v20, v178
	v_exp_f32_e32 v20, v20
	v_sub_f32_e32 v21, v21, v178
	v_exp_f32_e32 v21, v21
	v_sub_f32_e32 v22, v22, v178
	v_add_f32_e32 v179, 0, v18
	v_exp_f32_e32 v22, v22
	v_sub_f32_e32 v23, v23, v178
	v_add_f32_e32 v179, v19, v179
	v_exp_f32_e32 v23, v23
	v_sub_f32_e32 v24, v24, v178
	v_add_f32_e32 v179, v20, v179
	v_exp_f32_e32 v24, v24
	v_sub_f32_e32 v25, v25, v178
	v_add_f32_e32 v179, v21, v179
	v_exp_f32_e32 v25, v25
	v_sub_f32_e32 v26, v26, v178
	v_add_f32_e32 v179, v22, v179
	v_exp_f32_e32 v26, v26
	v_sub_f32_e32 v27, v27, v178
	v_add_f32_e32 v179, v23, v179
	v_exp_f32_e32 v27, v27
	v_sub_f32_e32 v28, v28, v178
	v_add_f32_e32 v179, v24, v179
	v_exp_f32_e32 v28, v28
	v_sub_f32_e32 v29, v29, v178
	v_add_f32_e32 v179, v25, v179
	v_exp_f32_e32 v29, v29
	v_sub_f32_e32 v30, v30, v178
	v_add_f32_e32 v179, v26, v179
	v_exp_f32_e32 v30, v30
	v_sub_f32_e32 v31, v31, v178
	v_add_f32_e32 v179, v27, v179
	v_exp_f32_e32 v31, v31
	v_sub_f32_e32 v32, v32, v178
	v_add_f32_e32 v179, v28, v179
	v_exp_f32_e32 v32, v32
	v_sub_f32_e32 v33, v33, v178
	v_add_f32_e32 v179, v29, v179
	v_exp_f32_e32 v33, v33
	v_sub_f32_e32 v50, v50, v178
	v_add_f32_e32 v179, v30, v179
	v_exp_f32_e32 v50, v50
	v_sub_f32_e32 v51, v51, v178
	v_add_f32_e32 v179, v31, v179
	v_exp_f32_e32 v51, v51
	v_sub_f32_e32 v52, v52, v178
	v_add_f32_e32 v179, v32, v179
	v_exp_f32_e32 v52, v52
	v_sub_f32_e32 v53, v53, v178
	v_add_f32_e32 v179, v33, v179
	v_exp_f32_e32 v53, v53
	v_sub_f32_e32 v54, v54, v178
	v_add_f32_e32 v179, v50, v179
	v_exp_f32_e32 v54, v54
	v_sub_f32_e32 v55, v55, v178
	v_add_f32_e32 v179, v51, v179
	v_exp_f32_e32 v55, v55
	v_sub_f32_e32 v56, v56, v178
	v_add_f32_e32 v179, v52, v179
	v_exp_f32_e32 v56, v56
	v_sub_f32_e32 v57, v57, v178
	v_add_f32_e32 v179, v53, v179
	v_exp_f32_e32 v57, v57
	v_sub_f32_e32 v58, v58, v178
	v_add_f32_e32 v179, v54, v179
	v_exp_f32_e32 v58, v58
	v_sub_f32_e32 v59, v59, v178
	v_add_f32_e32 v179, v55, v179
	v_exp_f32_e32 v59, v59
	v_sub_f32_e32 v60, v60, v178
	v_add_f32_e32 v179, v56, v179
	v_exp_f32_e32 v60, v60
	v_sub_f32_e32 v61, v61, v178
	v_add_f32_e32 v179, v57, v179
	v_exp_f32_e32 v61, v61
	v_sub_f32_e32 v62, v62, v178
	v_add_f32_e32 v179, v58, v179
	v_exp_f32_e32 v62, v62
	v_sub_f32_e32 v63, v63, v178
	v_add_f32_e32 v179, v59, v179
	v_exp_f32_e32 v63, v63
	v_sub_f32_e32 v64, v64, v178
	v_add_f32_e32 v179, v60, v179
	v_exp_f32_e32 v64, v64
	v_sub_f32_e32 v65, v65, v178
	v_add_f32_e32 v179, v61, v179
	v_exp_f32_e32 v65, v65
	v_add_f32_e32 v179, v62, v179
	v_add_f32_e32 v179, v63, v179
	v_add_f32_e32 v179, v64, v179
	v_add_f32_e32 v179, v65, v179
	v_add_f32_e32 v176, v176, v179
	v_cvt_pk_bf16_f32 v180, v18, v19
	v_cvt_pk_bf16_f32 v181, v20, v21
	v_cvt_pk_bf16_f32 v182, v22, v23
	v_cvt_pk_bf16_f32 v183, v24, v25
	v_cvt_pk_bf16_f32 v184, v26, v27
	v_cvt_pk_bf16_f32 v185, v28, v29
	v_cvt_pk_bf16_f32 v186, v30, v31
	v_cvt_pk_bf16_f32 v187, v32, v33
	v_cvt_pk_bf16_f32 v188, v50, v51
	v_cvt_pk_bf16_f32 v189, v52, v53
	v_cvt_pk_bf16_f32 v190, v54, v55
	v_cvt_pk_bf16_f32 v191, v56, v57
	v_cvt_pk_bf16_f32 v192, v58, v59
	v_cvt_pk_bf16_f32 v193, v60, v61
	v_cvt_pk_bf16_f32 v194, v62, v63
	v_cvt_pk_bf16_f32 v195, v64, v65
	s_waitcnt lgkmcnt(5)
	s_setprio 2
	v_mfma_f32_32x32x16_bf16 v[82:97], v[196:199], v[180:183], v[82:97]
	ds_read_b128 v[196:199], v222 offset:8192
	s_waitcnt lgkmcnt(5)
	v_mfma_f32_32x32x16_bf16 v[66:81], v[202:205], v[180:183], v[66:81]
	ds_read_b128 v[202:205], v222 offset:12288
	v_add_u32_e32 v222, v246, v175
	v_add_u32_e32 v179, v246, v177
	s_waitcnt lgkmcnt(5)
	v_mfma_f32_32x32x16_bf16 v[34:49], v[206:209], v[180:183], v[34:49]
	ds_read_b128 v[206:209], v222
	s_waitcnt lgkmcnt(5)
	v_mfma_f32_32x32x16_bf16 v[2:17], v[210:213], v[180:183], v[2:17]
	ds_read_b128 v[180:183], v222 offset:4096
	s_waitcnt lgkmcnt(5)
	v_mfma_f32_32x32x16_bf16 v[82:97], v[214:217], v[184:187], v[82:97]
	ds_read_b128 v[210:213], v222 offset:8192
	s_waitcnt lgkmcnt(5)
	v_mfma_f32_32x32x16_bf16 v[66:81], v[218:221], v[184:187], v[66:81]
	ds_read_b128 v[214:217], v222 offset:12288
	s_waitcnt lgkmcnt(5)
	v_mfma_f32_32x32x16_bf16 v[34:49], v[196:199], v[184:187], v[34:49]
	ds_read_b128 v[196:199], v179
	s_waitcnt lgkmcnt(5)
	v_mfma_f32_32x32x16_bf16 v[2:17], v[202:205], v[184:187], v[2:17]
	ds_read_b128 v[184:187], v179 offset:4096
	s_waitcnt lgkmcnt(5)
	v_mfma_f32_32x32x16_bf16 v[82:97], v[206:209], v[188:191], v[82:97]
	ds_read_b128 v[202:205], v179 offset:8192
	s_waitcnt lgkmcnt(5)
	v_mfma_f32_32x32x16_bf16 v[66:81], v[180:183], v[188:191], v[66:81]
	ds_read_b128 v[180:183], v179 offset:12288
	s_waitcnt lgkmcnt(5)
	v_mfma_f32_32x32x16_bf16 v[34:49], v[210:213], v[188:191], v[34:49]
	s_waitcnt lgkmcnt(4)
	v_mfma_f32_32x32x16_bf16 v[2:17], v[214:217], v[188:191], v[2:17]
	s_waitcnt lgkmcnt(3)
	v_mfma_f32_32x32x16_bf16 v[82:97], v[196:199], v[192:195], v[82:97]
	s_waitcnt lgkmcnt(2)
	v_mfma_f32_32x32x16_bf16 v[66:81], v[184:187], v[192:195], v[66:81]
	s_waitcnt lgkmcnt(1)
	v_mfma_f32_32x32x16_bf16 v[34:49], v[202:205], v[192:195], v[34:49]
	s_waitcnt lgkmcnt(0)
	v_mfma_f32_32x32x16_bf16 v[2:17], v[180:183], v[192:195], v[2:17]
	s_setprio 1
; #define LAS __attribute__((address_space(3)))
; template <bool MLA, bool grpB>
; __device__ __forceinline__ void attn_unit_g(LAS unsigned char* lds, const AttnPtrs& P, int b, int h, int qblk) {
;     ...
;     auto qk = [&](int koff) {
;         if (MLA) {
;         } else {
; #pragma unroll
;             for (int blk = 0; blk < 2; ++blk)
; #pragma unroll
;                 for (int g = 0; g < 4; ++g) { const f32x4 c4 = *(const LAS f32x4*)(lds + koff + KTILE + (32 * blk + 16 * hi + 4 * g) * 4);
; #pragma unroll
;                     for (int e = 0; e < 4; ++e) sc[blk][4 * g + e] = c4[e]; }
;         }
;         const LAS unsigned char* ka = lds + koff + karow;
;         bf16x8 a[PFD];
;         auto ld = [&](int i) -> bf16x8 {
;             const int d0 = i >> 1, blk = i & 1, seg = 2 * d0;
;             int so;
;             if (MLA) so = (((seg + hi) & 24) | (((seg + hi) ^ kswz) & 7)) * 16; else so = ((seg + hi) ^ kswz) * 16;
;             return *(const LAS bf16x8*)(ka + blk * 32 * KROW + so);
;         };
; #pragma unroll
;         for (int i = 0; i < PFD; ++i) a[i] = ld(i);
; #pragma unroll
;         for (int i = 0; i < 2 * ND0; ++i) {
;             const f32x16 zc = {0.f, 0.f, 0.f, 0.f, 0.f, 0.f, 0.f, 0.f, 0.f, 0.f, 0.f, 0.f, 0.f, 0.f, 0.f, 0.f};
;             sc[i & 1] = __builtin_amdgcn_mfma_f32_32x32x16_bf16(a[i % PFD], qf[i >> 1], (MLA && i < 2) ? zc : sc[i & 1], 0, 0, 0);
;             if (i + PFD < 2 * ND0) a[i % PFD] = ld(i + PFD);
;         }
;         __builtin_amdgcn_sched_group_barrier(0x100, PFD, 0);
; #pragma unroll
;         for (int i = 0; i < 2 * ND0; ++i) { __builtin_amdgcn_sched_group_barrier(0x008, 1, 0); __builtin_amdgcn_sched_group_barrier(0x100, 1, 0); }
;         __builtin_amdgcn_sched_barrier(0);
;     };
.LBB0_1152:
	s_cmp_eq_u32 s36, -3
	s_cselect_b64 s[26:27], -1, 0
	s_cmp_gt_i32 s16, s13
	s_cselect_b64 s[16:17], -1, 0
	s_or_b64 s[16:17], s[26:27], s[16:17]
	s_and_b64 vcc, exec, s[16:17]
	s_cbranch_vccnz .LBB0_1156
	v_add_u32_e32 v54, s23, v161
	v_add_u32_e32 v179, v54, v162
	ds_read_b128 v[18:21], v179
	ds_read_b128 v[50:53], v179 offset:12288
	v_add_u32_e32 v206, v54, v163
	v_add_u32_e32 v207, v54, v164
	ds_read_b128 v[180:183], v206
	ds_read_b128 v[184:187], v206 offset:12288
	v_add_u32_e32 v208, v54, v165
	ds_read_b128 v[188:191], v207
	ds_read_b128 v[192:195], v207 offset:12288
	s_waitcnt lgkmcnt(5)
	s_setprio 2
	v_mfma_f32_32x32x16_bf16 v[18:33], v[18:21], v[98:101], 0
	ds_read_b128 v[196:199], v208
	s_waitcnt lgkmcnt(5)
	v_mfma_f32_32x32x16_bf16 v[50:65], v[50:53], v[98:101], 0
	ds_read_b128 v[202:205], v208 offset:12288
	s_waitcnt lgkmcnt(5)
	v_mfma_f32_32x32x16_bf16 v[18:33], v[180:183], v[102:105], v[18:33]
	ds_read_b128 v[180:183], v179 offset:128
	s_waitcnt lgkmcnt(5)
	v_mfma_f32_32x32x16_bf16 v[50:65], v[184:187], v[102:105], v[50:65]
	ds_read_b128 v[184:187], v179 offset:12416
	s_waitcnt lgkmcnt(5)
	v_mfma_f32_32x32x16_bf16 v[18:33], v[188:191], v[106:109], v[18:33]
	ds_read_b128 v[188:191], v206 offset:128
	s_waitcnt lgkmcnt(5)
	v_mfma_f32_32x32x16_bf16 v[50:65], v[192:195], v[106:109], v[50:65]
	ds_read_b128 v[192:195], v206 offset:12416
	s_waitcnt lgkmcnt(5)
	v_mfma_f32_32x32x16_bf16 v[18:33], v[196:199], v[110:113], v[18:33]
	ds_read_b128 v[196:199], v207 offset:128
	s_waitcnt lgkmcnt(5)
	v_mfma_f32_32x32x16_bf16 v[50:65], v[202:205], v[110:113], v[50:65]
	ds_read_b128 v[202:205], v207 offset:12416
	s_waitcnt lgkmcnt(5)
	v_mfma_f32_32x32x16_bf16 v[18:33], v[180:183], v[114:117], v[18:33]
	ds_read_b128 v[180:183], v208 offset:128
	s_waitcnt lgkmcnt(5)
	v_mfma_f32_32x32x16_bf16 v[50:65], v[184:187], v[114:117], v[50:65]
	ds_read_b128 v[184:187], v208 offset:12416
	s_waitcnt lgkmcnt(5)
	v_mfma_f32_32x32x16_bf16 v[18:33], v[188:191], v[118:121], v[18:33]
	ds_read_b128 v[188:191], v179 offset:256
	s_waitcnt lgkmcnt(5)
	v_mfma_f32_32x32x16_bf16 v[50:65], v[192:195], v[118:121], v[50:65]
	ds_read_b128 v[192:195], v179 offset:12544
	s_waitcnt lgkmcnt(5)
	v_mfma_f32_32x32x16_bf16 v[18:33], v[196:199], v[122:125], v[18:33]
	ds_read_b128 v[196:199], v206 offset:256
	s_waitcnt lgkmcnt(5)
	v_mfma_f32_32x32x16_bf16 v[50:65], v[202:205], v[122:125], v[50:65]
	ds_read_b128 v[202:205], v206 offset:12544
	s_waitcnt lgkmcnt(5)
	v_mfma_f32_32x32x16_bf16 v[18:33], v[180:183], v[126:129], v[18:33]
	ds_read_b128 v[180:183], v207 offset:256
	s_waitcnt lgkmcnt(5)
	v_mfma_f32_32x32x16_bf16 v[50:65], v[184:187], v[126:129], v[50:65]
	ds_read_b128 v[184:187], v207 offset:12544
	s_waitcnt lgkmcnt(5)
	v_mfma_f32_32x32x16_bf16 v[18:33], v[188:191], v[130:133], v[18:33]
	ds_read_b128 v[188:191], v208 offset:256
	s_waitcnt lgkmcnt(5)
	v_mfma_f32_32x32x16_bf16 v[50:65], v[192:195], v[130:133], v[50:65]
	ds_read_b128 v[192:195], v208 offset:12544
	s_waitcnt lgkmcnt(5)
	v_mfma_f32_32x32x16_bf16 v[18:33], v[196:199], v[134:137], v[18:33]
	s_waitcnt lgkmcnt(4)
	v_mfma_f32_32x32x16_bf16 v[50:65], v[202:205], v[134:137], v[50:65]
	s_waitcnt lgkmcnt(3)
	v_mfma_f32_32x32x16_bf16 v[18:33], v[180:183], v[138:141], v[18:33]
	s_waitcnt lgkmcnt(2)
	v_mfma_f32_32x32x16_bf16 v[50:65], v[184:187], v[138:141], v[50:65]
	s_waitcnt lgkmcnt(1)
	v_mfma_f32_32x32x16_bf16 v[18:33], v[188:191], v[142:145], v[18:33]
	s_waitcnt lgkmcnt(0)
	v_mfma_f32_32x32x16_bf16 v[50:65], v[192:195], v[142:145], v[50:65]
	s_setprio 1
	s_mov_b64 s[16:17], -1
	s_and_b64 vcc, exec, s[14:15]
	s_cbranch_vccnz .LBB0_1157

; #define LAS __attribute__((address_space(3)))
; template <bool MLA, bool grpB>
; __device__ __forceinline__ void attn_unit_g(LAS unsigned char* lds, const AttnPtrs& P, int b, int h, int qblk) {
;     ...
;     auto qk = [&](int koff) {
;         if (MLA) {
;         } else {
; #pragma unroll
;             for (int blk = 0; blk < 2; ++blk)
; #pragma unroll
;                 for (int g = 0; g < 4; ++g) { const f32x4 c4 = *(const LAS f32x4*)(lds + koff + KTILE + (32 * blk + 16 * hi + 4 * g) * 4);
; #pragma unroll
;                     for (int e = 0; e < 4; ++e) sc[blk][4 * g + e] = c4[e]; }
;         }
;         const LAS unsigned char* ka = lds + koff + karow;
;         bf16x8 a[PFD];
;         auto ld = [&](int i) -> bf16x8 {
;             const int d0 = i >> 1, blk = i & 1, seg = 2 * d0;
;             int so;
;             if (MLA) so = (((seg + hi) & 24) | (((seg + hi) ^ kswz) & 7)) * 16; else so = ((seg + hi) ^ kswz) * 16;
;             return *(const LAS bf16x8*)(ka + blk * 32 * KROW + so);
;         };
; #pragma unroll
;         for (int i = 0; i < PFD; ++i) a[i] = ld(i);
; #pragma unroll
;         for (int i = 0; i < 2 * ND0; ++i) {
;             const f32x16 zc = {0.f, 0.f, 0.f, 0.f, 0.f, 0.f, 0.f, 0.f, 0.f, 0.f, 0.f, 0.f, 0.f, 0.f, 0.f, 0.f};
;             sc[i & 1] = __builtin_amdgcn_mfma_f32_32x32x16_bf16(a[i % PFD], qf[i >> 1], (MLA && i < 2) ? zc : sc[i & 1], 0, 0, 0);
;             if (i + PFD < 2 * ND0) a[i % PFD] = ld(i + PFD);
;         }
;         __builtin_amdgcn_sched_group_barrier(0x100, PFD, 0);
; #pragma unroll
;         for (int i = 0; i < 2 * ND0; ++i) { __builtin_amdgcn_sched_group_barrier(0x008, 1, 0); __builtin_amdgcn_sched_group_barrier(0x100, 1, 0); }
;         __builtin_amdgcn_sched_barrier(0);
;     };
;     float mref = -1e30f;
;     auto sm = [&](int j) {
;         if (j >= my_last) {
;             if (MLA) { if (j > my_last) {
; #pragma unroll
;                 for (int r = 0; r < 16; ++r) { sc[0][r] = -2e30f; sc[1][r] = -2e30f; } } }
;             else { const int qpos = q0 + r32;
; #pragma unroll
;                 for (int blk = 0; blk < 2; ++blk)
; #pragma unroll
;                     for (int r = 0; r < 16; ++r) { const int key = 64 * j + 32 * blk + 16 * hi + r; if (key > qpos) sc[blk][r] = -2e30f; } }
;         }
;         float big_ = 3.0e38f; asm volatile("" : "+v"(big_));
.LBB0_1214:
	v_add_u32_e32 v0, s26, v179
	v_add_u32_e32 v14, v0, v183
	ds_read_b128 v[2:5], v14
	ds_read_b128 v[6:9], v14 offset:12288
	v_add_u32_e32 v15, v0, v184
	v_add_u32_e32 v198, v0, v185
	ds_read_b128 v[10:13], v15
	ds_read_b128 v[194:197], v15 offset:12288
	v_add_u32_e32 v0, v0, v186
	ds_read_b128 v[202:205], v198
	ds_read_b128 v[206:209], v198 offset:12288
	s_waitcnt lgkmcnt(5)
	s_setprio 2
	v_mfma_f32_32x32x16_bf16 v[96:111], v[2:5], v[112:115], 0
	ds_read_b128 v[2:5], v0
	s_waitcnt lgkmcnt(5)
	v_mfma_f32_32x32x16_bf16 v[80:95], v[6:9], v[112:115], 0
	ds_read_b128 v[6:9], v0 offset:12288
	s_waitcnt lgkmcnt(5)
	v_mfma_f32_32x32x16_bf16 v[96:111], v[10:13], v[116:119], v[96:111]
	ds_read_b128 v[10:13], v14 offset:128
	s_waitcnt lgkmcnt(5)
	v_mfma_f32_32x32x16_bf16 v[80:95], v[194:197], v[116:119], v[80:95]
	ds_read_b128 v[194:197], v14 offset:12416
	s_waitcnt lgkmcnt(5)
	v_mfma_f32_32x32x16_bf16 v[96:111], v[202:205], v[120:123], v[96:111]
	ds_read_b128 v[202:205], v15 offset:128
	s_waitcnt lgkmcnt(5)
	v_mfma_f32_32x32x16_bf16 v[80:95], v[206:209], v[120:123], v[80:95]
	ds_read_b128 v[206:209], v15 offset:12416
	s_waitcnt lgkmcnt(5)
	v_mfma_f32_32x32x16_bf16 v[96:111], v[2:5], v[124:127], v[96:111]
	ds_read_b128 v[2:5], v198 offset:128
	s_waitcnt lgkmcnt(5)
	v_mfma_f32_32x32x16_bf16 v[80:95], v[6:9], v[124:127], v[80:95]
	ds_read_b128 v[6:9], v198 offset:12416
	s_waitcnt lgkmcnt(5)
	v_mfma_f32_32x32x16_bf16 v[96:111], v[10:13], v[128:131], v[96:111]
	ds_read_b128 v[10:13], v0 offset:128
	s_waitcnt lgkmcnt(5)
	v_mfma_f32_32x32x16_bf16 v[80:95], v[194:197], v[128:131], v[80:95]
	ds_read_b128 v[194:197], v0 offset:12416
	s_waitcnt lgkmcnt(5)
	v_mfma_f32_32x32x16_bf16 v[96:111], v[202:205], v[132:135], v[96:111]
	ds_read_b128 v[202:205], v14 offset:256
	s_waitcnt lgkmcnt(5)
	v_mfma_f32_32x32x16_bf16 v[80:95], v[206:209], v[132:135], v[80:95]
	ds_read_b128 v[206:209], v14 offset:12544
	s_waitcnt lgkmcnt(5)
	v_mfma_f32_32x32x16_bf16 v[96:111], v[2:5], v[136:139], v[96:111]
	ds_read_b128 v[2:5], v15 offset:256
	s_waitcnt lgkmcnt(5)
	v_mfma_f32_32x32x16_bf16 v[80:95], v[6:9], v[136:139], v[80:95]
	ds_read_b128 v[6:9], v15 offset:12544
	s_waitcnt lgkmcnt(5)
	v_mfma_f32_32x32x16_bf16 v[96:111], v[10:13], v[140:143], v[96:111]
	ds_read_b128 v[10:13], v198 offset:256
	s_waitcnt lgkmcnt(5)
	v_mfma_f32_32x32x16_bf16 v[80:95], v[194:197], v[140:143], v[80:95]
	ds_read_b128 v[194:197], v198 offset:12544
	s_waitcnt lgkmcnt(5)
	v_mfma_f32_32x32x16_bf16 v[96:111], v[202:205], v[144:147], v[96:111]
	ds_read_b128 v[202:205], v0 offset:256
	s_waitcnt lgkmcnt(5)
	v_mfma_f32_32x32x16_bf16 v[80:95], v[206:209], v[144:147], v[80:95]
	ds_read_b128 v[206:209], v0 offset:12544
	s_waitcnt lgkmcnt(5)
	v_mfma_f32_32x32x16_bf16 v[96:111], v[2:5], v[148:151], v[96:111]
	s_waitcnt lgkmcnt(4)
	v_mfma_f32_32x32x16_bf16 v[80:95], v[6:9], v[148:151], v[80:95]
	s_waitcnt lgkmcnt(3)
	v_mfma_f32_32x32x16_bf16 v[96:111], v[10:13], v[152:155], v[96:111]
	s_waitcnt lgkmcnt(2)
	v_mfma_f32_32x32x16_bf16 v[80:95], v[194:197], v[152:155], v[80:95]
	s_waitcnt lgkmcnt(1)
	v_mfma_f32_32x32x16_bf16 v[96:111], v[202:205], v[156:159], v[96:111]
	s_waitcnt lgkmcnt(0)
	v_mfma_f32_32x32x16_bf16 v[80:95], v[206:209], v[156:159], v[80:95]
	s_setprio 0
	v_mov_b32_e32 v0, 0x7f61b1e6
	s_nop 9
	v_med3_f32 v2, v96, v97, v0
	v_med3_f32 v6, v100, v101, v0
	v_med3_f32 v3, v98, v99, v0
	v_med3_f32 v2, v2, v6, v0
	v_med3_f32 v6, v102, v103, v0
	v_med3_f32 v4, v80, v81, v0
	v_med3_f32 v3, v3, v6, v0
	v_med3_f32 v6, v84, v85, v0
	v_med3_f32 v5, v82, v83, v0
	v_med3_f32 v4, v4, v6, v0
	v_med3_f32 v6, v86, v87, v0
	v_med3_f32 v5, v5, v6, v0
	v_med3_f32 v6, v104, v105, v0
	v_med3_f32 v2, v2, v6, v0
	v_med3_f32 v6, v106, v107, v0
	v_med3_f32 v3, v3, v6, v0
	v_med3_f32 v6, v88, v89, v0
	v_med3_f32 v4, v4, v6, v0
	v_med3_f32 v6, v90, v91, v0
	v_med3_f32 v5, v5, v6, v0
	v_med3_f32 v6, v108, v109, v0
	v_med3_f32 v2, v2, v6, v0
	v_med3_f32 v6, v110, v111, v0
	v_med3_f32 v3, v3, v6, v0
	v_med3_f32 v6, v92, v93, v0
	v_med3_f32 v4, v4, v6, v0
	v_med3_f32 v6, v94, v95, v0
	v_med3_f32 v5, v5, v6, v0
	v_med3_f32 v2, v2, v3, v0
	v_med3_f32 v3, v4, v5, v0
	v_and_b32_e32 v4, 64, v171
	v_med3_f32 v2, v2, v3, v0
	v_xor_b32_e32 v3, 32, v171
	v_add_u32_e32 v4, 64, v4
	v_cmp_lt_i32_e32 vcc, v3, v4
	s_nop 1
	v_cndmask_b32_e32 v3, v171, v3, vcc
	v_lshlrev_b32_e32 v3, 2, v3
	ds_bpermute_b32 v3, v3, v2
	s_waitcnt lgkmcnt(0)
	v_med3_f32 v0, v2, v3, v0
	v_add_f32_e32 v2, 0x41000000, v193
	v_cmp_gt_f32_e32 vcc, v0, v2
	s_cbranch_vccz .LBB0_1216
	v_max_f32_e32 v0, v0, v0
	v_max_f32_e32 v2, v193, v193
	v_max_f32_e32 v2, v2, v0
	v_sub_f32_e32 v0, v193, v2
	v_exp_f32_e32 v0, v0
	v_mov_b32_e32 v193, v2
	v_mul_f32_e32 v192, v192, v0
	v_pk_mul_f32 v[78:79], v[78:79], v[0:1] op_sel_hi:[1,0]
	v_pk_mul_f32 v[76:77], v[76:77], v[0:1] op_sel_hi:[1,0]
	v_pk_mul_f32 v[74:75], v[74:75], v[0:1] op_sel_hi:[1,0]
	v_pk_mul_f32 v[72:73], v[72:73], v[0:1] op_sel_hi:[1,0]
	v_pk_mul_f32 v[70:71], v[70:71], v[0:1] op_sel_hi:[1,0]
	v_pk_mul_f32 v[68:69], v[68:69], v[0:1] op_sel_hi:[1,0]
	v_pk_mul_f32 v[66:67], v[66:67], v[0:1] op_sel_hi:[1,0]
	v_pk_mul_f32 v[64:65], v[64:65], v[0:1] op_sel_hi:[1,0]
	v_pk_mul_f32 v[62:63], v[62:63], v[0:1] op_sel_hi:[1,0]
	v_pk_mul_f32 v[60:61], v[60:61], v[0:1] op_sel_hi:[1,0]
	v_pk_mul_f32 v[58:59], v[58:59], v[0:1] op_sel_hi:[1,0]
	v_pk_mul_f32 v[56:57], v[56:57], v[0:1] op_sel_hi:[1,0]
	v_pk_mul_f32 v[54:55], v[54:55], v[0:1] op_sel_hi:[1,0]
	v_pk_mul_f32 v[52:53], v[52:53], v[0:1] op_sel_hi:[1,0]
	v_pk_mul_f32 v[50:51], v[50:51], v[0:1] op_sel_hi:[1,0]
	v_pk_mul_f32 v[48:49], v[48:49], v[0:1] op_sel_hi:[1,0]
	v_pk_mul_f32 v[46:47], v[46:47], v[0:1] op_sel_hi:[1,0]
	v_pk_mul_f32 v[44:45], v[44:45], v[0:1] op_sel_hi:[1,0]
	v_pk_mul_f32 v[42:43], v[42:43], v[0:1] op_sel_hi:[1,0]
	v_pk_mul_f32 v[40:41], v[40:41], v[0:1] op_sel_hi:[1,0]
	v_pk_mul_f32 v[38:39], v[38:39], v[0:1] op_sel_hi:[1,0]
	v_pk_mul_f32 v[36:37], v[36:37], v[0:1] op_sel_hi:[1,0]
	v_pk_mul_f32 v[34:35], v[34:35], v[0:1] op_sel_hi:[1,0]
	v_pk_mul_f32 v[32:33], v[32:33], v[0:1] op_sel_hi:[1,0]
	v_pk_mul_f32 v[30:31], v[30:31], v[0:1] op_sel_hi:[1,0]
	v_pk_mul_f32 v[28:29], v[28:29], v[0:1] op_sel_hi:[1,0]
	v_pk_mul_f32 v[26:27], v[26:27], v[0:1] op_sel_hi:[1,0]
	v_pk_mul_f32 v[24:25], v[24:25], v[0:1] op_sel_hi:[1,0]
	v_pk_mul_f32 v[22:23], v[22:23], v[0:1] op_sel_hi:[1,0]
	v_pk_mul_f32 v[20:21], v[20:21], v[0:1] op_sel_hi:[1,0]
	v_pk_mul_f32 v[18:19], v[18:19], v[0:1] op_sel_hi:[1,0]
	v_pk_mul_f32 v[16:17], v[16:17], v[0:1] op_sel_hi:[1,0]
; __device__ __forceinline__ unsigned cvt_pk_bf16(float lo, float hi) { unsigned r; asm volatile("v_cvt_pk_bf16_f32 %0, %1, %2" : "=v"(r) : "v"(lo), "v"(hi)); return r; }
; #define LAS __attribute__((address_space(3)))
; template <bool MLA, bool grpB>
; __device__ __forceinline__ void attn_unit_g(LAS unsigned char* lds, const AttnPtrs& P, int b, int h, int qblk) {
;     ...
;         float ps = 0.f;
; #pragma unroll
;         for (int blk = 0; blk < 2; ++blk)
; #pragma unroll
;             for (int r = 0; r < 16; ++r) { const float pv_ = __builtin_amdgcn_exp2f(sc[blk][r] - mref); sc[blk][r] = pv_; ps += pv_; }
;         lrun += ps;
; #pragma unroll
;         for (int blk = 0; blk < 2; ++blk)
; #pragma unroll
;             for (int ks = 0; ks < 2; ++ks) { u32x4 w;
;                 w.x = pg8::cvt_pk_bf16(sc[blk][8 * ks + 0], sc[blk][8 * ks + 1]); w.y = pg8::cvt_pk_bf16(sc[blk][8 * ks + 2], sc[blk][8 * ks + 3]);
;                 w.z = pg8::cvt_pk_bf16(sc[blk][8 * ks + 4], sc[blk][8 * ks + 5]); w.w = pg8::cvt_pk_bf16(sc[blk][8 * ks + 6], sc[blk][8 * ks + 7]);
;                 pb[blk][ks] = __builtin_bit_cast(bf16x8, w); }
;         __builtin_amdgcn_sched_barrier(0);
;     };
;     auto pv = [&](int voff) {
;         const LAS unsigned char* va = lds + varow + voff;
;         bf16x8 a[PFD];
;         auto ld = [&](int i) -> bf16x8 {
;             const int dvb = i & 3, bk = i >> 2, so = ((4 * (bk >> 1) + 2 * hi + (bk & 1)) ^ vswz) * 16;
;             return *(const LAS bf16x8*)(va + 32 * dvb * VROW + so);
;         };
; #pragma unroll
;         for (int i = 0; i < PFD; ++i) a[i] = ld(i);
; #pragma unroll
;         for (int i = 0; i < 16; ++i) {
;             o[i & 3] = __builtin_amdgcn_mfma_f32_32x32x16_bf16(a[i % PFD], pb[i >> 3][(i >> 2) & 1], o[i & 3], 0, 0, 0);
;             if (i + PFD < 16) a[i % PFD] = ld(i + PFD);
;         }
;         __builtin_amdgcn_sched_group_barrier(0x100, PFD, 0);
; #pragma unroll
;         for (int i = 0; i < 16; ++i) { __builtin_amdgcn_sched_group_barrier(0x008, 1, 0); __builtin_amdgcn_sched_group_barrier(0x100, 1, 0); }
;         __builtin_amdgcn_sched_barrier(0);
.LBB0_1216:
	v_sub_f32_e32 v0, v96, v193
	v_exp_f32_e32 v0, v0
	v_sub_f32_e32 v2, v97, v193
	v_exp_f32_e32 v2, v2
	v_sub_f32_e32 v3, v98, v193
	v_exp_f32_e32 v3, v3
	v_sub_f32_e32 v4, v99, v193
	v_exp_f32_e32 v4, v4
	v_sub_f32_e32 v6, v100, v193
	v_add_f32_e32 v5, 0, v0
	v_exp_f32_e32 v6, v6
	v_sub_f32_e32 v7, v101, v193
	v_add_f32_e32 v5, v2, v5
	v_exp_f32_e32 v7, v7
	v_sub_f32_e32 v8, v102, v193
	v_add_f32_e32 v5, v3, v5
	v_exp_f32_e32 v8, v8
	v_sub_f32_e32 v9, v103, v193
	v_add_f32_e32 v5, v4, v5
	v_exp_f32_e32 v9, v9
	v_sub_f32_e32 v10, v104, v193
	v_add_f32_e32 v5, v6, v5
	v_exp_f32_e32 v10, v10
	v_sub_f32_e32 v11, v105, v193
	v_add_f32_e32 v5, v7, v5
	v_exp_f32_e32 v11, v11
	v_sub_f32_e32 v12, v106, v193
	v_add_f32_e32 v5, v8, v5
	v_exp_f32_e32 v12, v12
	v_sub_f32_e32 v13, v107, v193
	v_add_f32_e32 v5, v9, v5
	v_exp_f32_e32 v13, v13
	v_sub_f32_e32 v14, v108, v193
	v_add_f32_e32 v5, v10, v5
	v_exp_f32_e32 v14, v14
	v_sub_f32_e32 v15, v109, v193
	v_add_f32_e32 v5, v11, v5
	v_exp_f32_e32 v15, v15
	v_sub_f32_e32 v96, v110, v193
	v_add_f32_e32 v5, v12, v5
	v_exp_f32_e32 v96, v96
	v_sub_f32_e32 v97, v111, v193
	v_add_f32_e32 v5, v13, v5
	v_exp_f32_e32 v97, v97
	v_sub_f32_e32 v80, v80, v193
	v_add_f32_e32 v5, v14, v5
	v_exp_f32_e32 v80, v80
	v_sub_f32_e32 v81, v81, v193
	v_add_f32_e32 v5, v15, v5
	v_exp_f32_e32 v81, v81
	v_sub_f32_e32 v82, v82, v193
	v_add_f32_e32 v5, v96, v5
	v_exp_f32_e32 v82, v82
	v_sub_f32_e32 v83, v83, v193
	v_add_f32_e32 v5, v97, v5
	v_exp_f32_e32 v83, v83
	v_sub_f32_e32 v84, v84, v193
	v_add_f32_e32 v5, v80, v5
	v_exp_f32_e32 v84, v84
	v_sub_f32_e32 v85, v85, v193
	v_add_f32_e32 v5, v81, v5
	v_exp_f32_e32 v85, v85
	v_sub_f32_e32 v86, v86, v193
	v_add_f32_e32 v5, v82, v5
	v_exp_f32_e32 v86, v86
	v_sub_f32_e32 v87, v87, v193
	v_add_f32_e32 v5, v83, v5
	v_exp_f32_e32 v87, v87
	v_sub_f32_e32 v88, v88, v193
	v_add_f32_e32 v5, v84, v5
	v_exp_f32_e32 v88, v88
	v_sub_f32_e32 v89, v89, v193
	v_add_f32_e32 v5, v85, v5
	v_exp_f32_e32 v89, v89
	v_sub_f32_e32 v90, v90, v193
	v_add_f32_e32 v5, v86, v5
	v_exp_f32_e32 v90, v90
	v_sub_f32_e32 v91, v91, v193
	v_add_f32_e32 v5, v87, v5
	v_exp_f32_e32 v91, v91
	v_sub_f32_e32 v92, v92, v193
	v_add_f32_e32 v5, v88, v5
	v_exp_f32_e32 v92, v92
	v_sub_f32_e32 v93, v93, v193
	v_add_f32_e32 v5, v89, v5
	v_exp_f32_e32 v93, v93
	v_sub_f32_e32 v94, v94, v193
	v_add_f32_e32 v5, v90, v5
	v_exp_f32_e32 v94, v94
	v_sub_f32_e32 v95, v95, v193
	v_add_f32_e32 v5, v91, v5
	v_exp_f32_e32 v95, v95
	v_add_f32_e32 v5, v92, v5
	v_add_f32_e32 v5, v93, v5
	v_add_f32_e32 v5, v94, v5
	v_add_f32_e32 v5, v95, v5
	v_add_f32_e32 v192, v192, v5
	v_cvt_pk_bf16_f32 v2, v0, v2
	v_cvt_pk_bf16_f32 v3, v3, v4
	v_cvt_pk_bf16_f32 v4, v6, v7
	v_cvt_pk_bf16_f32 v5, v8, v9
	v_cvt_pk_bf16_f32 v6, v10, v11
	v_cvt_pk_bf16_f32 v7, v12, v13
	v_cvt_pk_bf16_f32 v8, v14, v15
	v_cvt_pk_bf16_f32 v9, v96, v97
	v_cvt_pk_bf16_f32 v10, v80, v81
	v_cvt_pk_bf16_f32 v11, v82, v83
	v_cvt_pk_bf16_f32 v12, v84, v85
	v_cvt_pk_bf16_f32 v13, v86, v87
	v_cvt_pk_bf16_f32 v80, v88, v89
	v_cvt_pk_bf16_f32 v81, v90, v91
	v_cvt_pk_bf16_f32 v82, v92, v93
	v_cvt_pk_bf16_f32 v83, v94, v95
	v_add_u32_e32 v0, s21, v187
	v_add_u32_e32 v14, v0, v188
	ds_read_b128 v[84:87], v14
	ds_read_b128 v[88:91], v14 offset:4096
	ds_read_b128 v[92:95], v14 offset:8192
	ds_read_b128 v[96:99], v14 offset:12288
	v_add_u32_e32 v15, v0, v189
	ds_read_b128 v[100:103], v15
	ds_read_b128 v[104:107], v15 offset:4096
	v_add_u32_e32 v14, v0, v190
	v_add_u32_e32 v0, v0, v191
	s_waitcnt lgkmcnt(5)
	s_setprio 2
	v_mfma_f32_32x32x16_bf16 v[64:79], v[84:87], v[2:5], v[64:79]
	ds_read_b128 v[84:87], v15 offset:8192
	s_waitcnt lgkmcnt(5)
	v_mfma_f32_32x32x16_bf16 v[48:63], v[88:91], v[2:5], v[48:63]
	ds_read_b128 v[88:91], v15 offset:12288
	s_waitcnt lgkmcnt(5)
	v_mfma_f32_32x32x16_bf16 v[32:47], v[92:95], v[2:5], v[32:47]
	ds_read_b128 v[92:95], v14
	s_waitcnt lgkmcnt(5)
	v_mfma_f32_32x32x16_bf16 v[16:31], v[96:99], v[2:5], v[16:31]
	ds_read_b128 v[2:5], v14 offset:4096
	s_waitcnt lgkmcnt(5)
	v_mfma_f32_32x32x16_bf16 v[64:79], v[100:103], v[6:9], v[64:79]
	ds_read_b128 v[96:99], v14 offset:8192
	s_waitcnt lgkmcnt(5)
	v_mfma_f32_32x32x16_bf16 v[48:63], v[104:107], v[6:9], v[48:63]
	ds_read_b128 v[100:103], v14 offset:12288
	s_waitcnt lgkmcnt(5)
	v_mfma_f32_32x32x16_bf16 v[32:47], v[84:87], v[6:9], v[32:47]
	ds_read_b128 v[84:87], v0
	s_waitcnt lgkmcnt(5)
	v_mfma_f32_32x32x16_bf16 v[16:31], v[88:91], v[6:9], v[16:31]
	ds_read_b128 v[6:9], v0 offset:4096
	s_waitcnt lgkmcnt(5)
	v_mfma_f32_32x32x16_bf16 v[64:79], v[92:95], v[10:13], v[64:79]
	ds_read_b128 v[88:91], v0 offset:8192
	s_waitcnt lgkmcnt(5)
	v_mfma_f32_32x32x16_bf16 v[48:63], v[2:5], v[10:13], v[48:63]
	ds_read_b128 v[2:5], v0 offset:12288
	s_waitcnt lgkmcnt(5)
	v_mfma_f32_32x32x16_bf16 v[32:47], v[96:99], v[10:13], v[32:47]
	s_waitcnt lgkmcnt(4)
	v_mfma_f32_32x32x16_bf16 v[16:31], v[100:103], v[10:13], v[16:31]
	s_waitcnt lgkmcnt(3)
	v_mfma_f32_32x32x16_bf16 v[64:79], v[84:87], v[80:83], v[64:79]
	s_waitcnt lgkmcnt(2)
	v_mfma_f32_32x32x16_bf16 v[48:63], v[6:9], v[80:83], v[48:63]
	s_waitcnt lgkmcnt(1)
	v_mfma_f32_32x32x16_bf16 v[32:47], v[88:91], v[80:83], v[32:47]
	s_waitcnt lgkmcnt(0)
	v_mfma_f32_32x32x16_bf16 v[16:31], v[2:5], v[80:83], v[16:31]
	s_setprio 0
	s_mov_b64 s[16:17], -1
	s_and_b64 vcc, exec, s[14:15]
	s_cbranch_vccnz .LBB0_1208

; #define LAS __attribute__((address_space(3)))
; template <bool MLA, bool grpB>
; __device__ __forceinline__ void attn_unit_g(LAS unsigned char* lds, const AttnPtrs& P, int b, int h, int qblk) {
;     ...
;     auto qk = [&](int koff) {
;         if (MLA) {
;         } else {
; #pragma unroll
;             for (int blk = 0; blk < 2; ++blk)
; #pragma unroll
;                 for (int g = 0; g < 4; ++g) { const f32x4 c4 = *(const LAS f32x4*)(lds + koff + KTILE + (32 * blk + 16 * hi + 4 * g) * 4);
; #pragma unroll
;                     for (int e = 0; e < 4; ++e) sc[blk][4 * g + e] = c4[e]; }
;         }
;         const LAS unsigned char* ka = lds + koff + karow;
;         bf16x8 a[PFD];
;         auto ld = [&](int i) -> bf16x8 {
;             const int d0 = i >> 1, blk = i & 1, seg = 2 * d0;
;             int so;
;             if (MLA) so = (((seg + hi) & 24) | (((seg + hi) ^ kswz) & 7)) * 16; else so = ((seg + hi) ^ kswz) * 16;
;             return *(const LAS bf16x8*)(ka + blk * 32 * KROW + so);
;         };
; #pragma unroll
;         for (int i = 0; i < PFD; ++i) a[i] = ld(i);
; #pragma unroll
;         for (int i = 0; i < 2 * ND0; ++i) {
;             const f32x16 zc = {0.f, 0.f, 0.f, 0.f, 0.f, 0.f, 0.f, 0.f, 0.f, 0.f, 0.f, 0.f, 0.f, 0.f, 0.f, 0.f};
;             sc[i & 1] = __builtin_amdgcn_mfma_f32_32x32x16_bf16(a[i % PFD], qf[i >> 1], (MLA && i < 2) ? zc : sc[i & 1], 0, 0, 0);
;             if (i + PFD < 2 * ND0) a[i % PFD] = ld(i + PFD);
;         }
;         __builtin_amdgcn_sched_group_barrier(0x100, PFD, 0);
; #pragma unroll
;         for (int i = 0; i < 2 * ND0; ++i) { __builtin_amdgcn_sched_group_barrier(0x008, 1, 0); __builtin_amdgcn_sched_group_barrier(0x100, 1, 0); }
;         __builtin_amdgcn_sched_barrier(0);
;     };
;     ...
;     dma_k(jl, 0); dma_v(jl, 0); dma_k(jl - 1, KSLOT);
;     dma_k(jl - 2, 2 * KSLOT); dma_v(jl - 1, VTILE);
;     if (MLA) asm volatile("s_waitcnt vmcnt(5)\n\ts_barrier" ::: "memory"); else asm volatile("s_waitcnt vmcnt(4)\n\ts_barrier" ::: "memory");
;     if (grpB) qk(0);
.LBB0_1252:
	s_or_b64 exec, exec, s[10:11]
	v_lshrrev_b32_e32 v8, 1, v3
	v_and_b32_e32 v5, 3, v3
	v_and_b32_e32 v6, 12, v8
	v_lshlrev_b32_e32 v4, 2, v2
	v_or_b32_e32 v7, v6, v5
	v_and_or_b32 v4, v4, 16, v7
	v_bitop3_b32 v9, v6, 7, v5 bitop3:0xc8
	v_lshlrev_b32_e32 v5, 1, v2
	s_lshl_b64 s[10:11], s[64:65], 7
	v_and_b32_e32 v10, 8, v5
	v_lshlrev_b32_e32 v147, 8, v4
	v_lshl_add_u64 v[4:5], v[152:153], 0, s[10:11]
	s_add_i32 m0, s95, 0x14400
	v_lshlrev_b32_e32 v161, 6, v160
	global_load_lds_dwordx4 v[4:5], off
	v_lshl_add_u64 v[4:5], v[154:155], 0, s[10:11]
	s_add_i32 m0, s95, 0x16400
	v_add_u32_e32 v11, 0, v147
	global_load_lds_dwordx4 v[4:5], off
	s_waitcnt vmcnt(4)
	s_barrier
	v_add_u32_e32 v4, 0, v161
	ds_read_b128 v[16:19], v4 offset:16384
	ds_read_b128 v[20:23], v4 offset:16400
	ds_read_b128 v[24:27], v4 offset:16416
	ds_read_b128 v[28:31], v4 offset:16432
	ds_read_b128 v[32:35], v4 offset:16512
	ds_read_b128 v[36:39], v4 offset:16528
	ds_read_b128 v[40:43], v4 offset:16544
	ds_read_b128 v[44:47], v4 offset:16560
	v_bitop3_b32 v4, v9, v160, v10 bitop3:0x36
	v_lshlrev_b32_e32 v162, 4, v4
	v_add_u32_e32 v12, v11, v162
	ds_read_b128 v[4:7], v12 offset:8192
	v_or_b32_e32 v13, 2, v160
	v_bitop3_b32 v13, v9, v13, v10 bitop3:0x36
	v_lshlrev_b32_e32 v163, 4, v13
	v_add_u32_e32 v13, v11, v163
	s_waitcnt vmcnt(0) lgkmcnt(0)
	v_mfma_f32_32x32x16_bf16 v[32:47], v[4:7], v[136:139], v[32:47]
	ds_read_b128 v[4:7], v13 offset:8192
	v_or_b32_e32 v14, 4, v160
	v_bitop3_b32 v14, v9, v14, v10 bitop3:0x36
	v_lshlrev_b32_e32 v164, 4, v14
	v_add_u32_e32 v14, v11, v164
	v_or_b32_e32 v15, 6, v160
	v_bitop3_b32 v15, v9, v15, v10 bitop3:0x36
	s_waitcnt lgkmcnt(0)
	v_mfma_f32_32x32x16_bf16 v[32:47], v[4:7], v[112:115], v[32:47]
	ds_read_b128 v[4:7], v14 offset:8192
	v_lshlrev_b32_e32 v165, 4, v15
	v_add_u32_e32 v15, v11, v165
	v_or_b32_e32 v48, 8, v160
	v_bitop3_b32 v48, v9, v48, v10 bitop3:0x36
	v_lshlrev_b32_e32 v166, 4, v48
	v_add_u32_e32 v48, v11, v166
	s_waitcnt lgkmcnt(0)
	v_mfma_f32_32x32x16_bf16 v[32:47], v[4:7], v[116:119], v[32:47]
	ds_read_b128 v[4:7], v15 offset:8192
	v_or_b32_e32 v49, 10, v160
	v_bitop3_b32 v49, v9, v49, v10 bitop3:0x36
	v_lshlrev_b32_e32 v167, 4, v49
	v_add_u32_e32 v49, v11, v167
	v_or_b32_e32 v50, 12, v160
	v_bitop3_b32 v50, v9, v50, v10 bitop3:0x36
	s_waitcnt lgkmcnt(0)
	v_mfma_f32_32x32x16_bf16 v[32:47], v[4:7], v[120:123], v[32:47]
	ds_read_b128 v[4:7], v48 offset:8192
	v_lshlrev_b32_e32 v168, 4, v50
	v_add_u32_e32 v50, v11, v168
	v_or_b32_e32 v51, 14, v160
	v_bitop3_b32 v9, v9, v51, v10 bitop3:0x36
	v_lshlrev_b32_e32 v169, 4, v9
	v_add_u32_e32 v9, v11, v169
	s_waitcnt lgkmcnt(0)
	v_mfma_f32_32x32x16_bf16 v[32:47], v[4:7], v[124:127], v[32:47]
	ds_read_b128 v[4:7], v49 offset:8192
	s_ashr_i32 s78, s14, 6
	v_bfe_u32 v3, v3, 1, 3
	s_waitcnt lgkmcnt(0)
	s_setprio 2
	v_mfma_f32_32x32x16_bf16 v[32:47], v[4:7], v[128:131], v[32:47]
	ds_read_b128 v[4:7], v50 offset:8192
	s_waitcnt lgkmcnt(0)
	v_mfma_f32_32x32x16_bf16 v[32:47], v[4:7], v[132:135], v[32:47]
	ds_read_b128 v[4:7], v9 offset:8192
	s_waitcnt lgkmcnt(0)
	v_mfma_f32_32x32x16_bf16 v[32:47], v[4:7], v[140:143], v[32:47]
	ds_read_b128 v[4:7], v12
	s_waitcnt lgkmcnt(0)
	v_mfma_f32_32x32x16_bf16 v[16:31], v[4:7], v[136:139], v[16:31]
	ds_read_b128 v[4:7], v13
	s_waitcnt lgkmcnt(0)
	v_mfma_f32_32x32x16_bf16 v[16:31], v[4:7], v[112:115], v[16:31]
	ds_read_b128 v[4:7], v14
	s_waitcnt lgkmcnt(0)
	v_mfma_f32_32x32x16_bf16 v[16:31], v[4:7], v[116:119], v[16:31]
	ds_read_b128 v[4:7], v15
	s_waitcnt lgkmcnt(0)
	v_mfma_f32_32x32x16_bf16 v[16:31], v[4:7], v[120:123], v[16:31]
	ds_read_b128 v[4:7], v48
	s_waitcnt lgkmcnt(0)
	v_mfma_f32_32x32x16_bf16 v[16:31], v[4:7], v[124:127], v[16:31]
	ds_read_b128 v[4:7], v49
	s_waitcnt lgkmcnt(0)
	v_mfma_f32_32x32x16_bf16 v[16:31], v[4:7], v[128:131], v[16:31]
	ds_read_b128 v[4:7], v50
	s_waitcnt lgkmcnt(0)
	v_mfma_f32_32x32x16_bf16 v[16:31], v[4:7], v[132:135], v[16:31]
	ds_read_b128 v[4:7], v9
	s_waitcnt lgkmcnt(0)
	v_mfma_f32_32x32x16_bf16 v[16:31], v[4:7], v[140:143], v[16:31]
	s_setprio 1
	v_lshl_add_u64 v[156:157], v[0:1], 2, s[8:9]
	v_lshl_add_u32 v0, v2, 7, 0
	v_add_u32_e32 v175, 0x10400, v0
	v_lshlrev_b32_e32 v0, 1, v160
	v_or_b32_e32 v173, s14, v2
	v_bitop3_b32 v2, v0, v8, 7 bitop3:0x78
	v_lshlrev_b32_e32 v176, 4, v2
	v_bitop3_b32 v2, v0, v3, 1 bitop3:0x36
	v_lshlrev_b32_e32 v177, 4, v2
	v_bitop3_b32 v2, v0, v3, 4 bitop3:0x36
	v_bitop3_b32 v0, v0, v3, 5 bitop3:0x36
	v_mov_b32_e32 v14, v1
	v_mov_b32_e32 v15, v1
	v_lshlrev_b32_e32 v178, 4, v2
	v_lshlrev_b32_e32 v179, 4, v0
	v_mov_b32_e32 v0, v1
	v_mov_b32_e32 v2, v1
	v_mov_b32_e32 v3, v1
	v_mov_b32_e32 v4, v1
	v_mov_b32_e32 v5, v1
	v_mov_b32_e32 v6, v1
	v_mov_b32_e32 v7, v1
	v_mov_b32_e32 v8, v1
	v_mov_b32_e32 v9, v1
	v_mov_b32_e32 v10, v1
	v_mov_b32_e32 v11, v1
	v_mov_b32_e32 v12, v1
	v_mov_b32_e32 v13, v1
	v_mov_b64_e32 v[62:63], v[14:15]
	v_mov_b64_e32 v[78:79], v[14:15]
	v_mov_b64_e32 v[94:95], v[14:15]
	v_mov_b64_e32 v[110:111], v[14:15]
	s_add_i32 s97, s78, 1
	s_mov_b32 s54, 0
	v_mov_b32_e32 v181, 0xf149f2ca
	s_movk_i32 s50, 0x4100
	s_mov_b32 s55, 0x8200
	s_mov_b32 s9, 0xc300
	s_movk_i32 s57, 0x4000
	s_mov_b32 s8, 0x8000
	v_mov_b32_e32 v180, 0
	s_mov_b32 s89, s40
	s_mov_b32 s64, s90
	v_mov_b64_e32 v[60:61], v[12:13]
	v_mov_b64_e32 v[58:59], v[10:11]
	v_mov_b64_e32 v[56:57], v[8:9]
	v_mov_b64_e32 v[54:55], v[6:7]
	v_mov_b64_e32 v[52:53], v[4:5]
	v_mov_b64_e32 v[50:51], v[2:3]
	v_mov_b64_e32 v[48:49], v[0:1]
	v_mov_b64_e32 v[76:77], v[12:13]
	v_mov_b64_e32 v[74:75], v[10:11]
	v_mov_b64_e32 v[72:73], v[8:9]
	v_mov_b64_e32 v[70:71], v[6:7]
	v_mov_b64_e32 v[68:69], v[4:5]
	v_mov_b64_e32 v[66:67], v[2:3]
	v_mov_b64_e32 v[64:65], v[0:1]
	v_mov_b64_e32 v[92:93], v[12:13]
	v_mov_b64_e32 v[90:91], v[10:11]
	v_mov_b64_e32 v[88:89], v[8:9]
	v_mov_b64_e32 v[86:87], v[6:7]
	v_mov_b64_e32 v[84:85], v[4:5]
	v_mov_b64_e32 v[82:83], v[2:3]
	v_mov_b64_e32 v[80:81], v[0:1]
	v_mov_b64_e32 v[108:109], v[12:13]
	v_mov_b64_e32 v[106:107], v[10:11]
	v_mov_b64_e32 v[104:105], v[8:9]
	v_mov_b64_e32 v[102:103], v[6:7]
	v_mov_b64_e32 v[100:101], v[4:5]
	v_mov_b64_e32 v[98:99], v[2:3]
	v_mov_b64_e32 v[96:97], v[0:1]
	s_mov_b32 s41, 0

; __device__ __forceinline__ unsigned cvt_pk_bf16(float lo, float hi) { unsigned r; asm volatile("v_cvt_pk_bf16_f32 %0, %1, %2" : "=v"(r) : "v"(lo), "v"(hi)); return r; }
; #define LAS __attribute__((address_space(3)))
; template <bool MLA, bool grpB>
; __device__ __forceinline__ void attn_unit_g(LAS unsigned char* lds, const AttnPtrs& P, int b, int h, int qblk) {
;     ...
;         float ps = 0.f;
; #pragma unroll
;         for (int blk = 0; blk < 2; ++blk)
; #pragma unroll
;             for (int r = 0; r < 16; ++r) { const float pv_ = __builtin_amdgcn_exp2f(sc[blk][r] - mref); sc[blk][r] = pv_; ps += pv_; }
;         lrun += ps;
; #pragma unroll
;         for (int blk = 0; blk < 2; ++blk)
; #pragma unroll
;             for (int ks = 0; ks < 2; ++ks) { u32x4 w;
;                 w.x = pg8::cvt_pk_bf16(sc[blk][8 * ks + 0], sc[blk][8 * ks + 1]); w.y = pg8::cvt_pk_bf16(sc[blk][8 * ks + 2], sc[blk][8 * ks + 3]);
;                 w.z = pg8::cvt_pk_bf16(sc[blk][8 * ks + 4], sc[blk][8 * ks + 5]); w.w = pg8::cvt_pk_bf16(sc[blk][8 * ks + 6], sc[blk][8 * ks + 7]);
;                 pb[blk][ks] = __builtin_bit_cast(bf16x8, w); }
;         __builtin_amdgcn_sched_barrier(0);
;     };
;     auto pv = [&](int voff) {
;         const LAS unsigned char* va = lds + varow + voff;
;         bf16x8 a[PFD];
;         auto ld = [&](int i) -> bf16x8 {
;             const int dvb = i & 3, bk = i >> 2, so = ((4 * (bk >> 1) + 2 * hi + (bk & 1)) ^ vswz) * 16;
;             return *(const LAS bf16x8*)(va + 32 * dvb * VROW + so);
;         };
; #pragma unroll
;         for (int i = 0; i < PFD; ++i) a[i] = ld(i);
; #pragma unroll
;         for (int i = 0; i < 16; ++i) {
;             o[i & 3] = __builtin_amdgcn_mfma_f32_32x32x16_bf16(a[i % PFD], pb[i >> 3][(i >> 2) & 1], o[i & 3], 0, 0, 0);
;             if (i + PFD < 16) a[i % PFD] = ld(i + PFD);
;         }
;         __builtin_amdgcn_sched_group_barrier(0x100, PFD, 0);
; #pragma unroll
;         for (int i = 0; i < 16; ++i) { __builtin_amdgcn_sched_group_barrier(0x008, 1, 0); __builtin_amdgcn_sched_group_barrier(0x100, 1, 0); }
;         __builtin_amdgcn_sched_barrier(0);
.LBB0_1268:
	v_add_u32_e32 v246, s54, v175
	v_add_u32_e32 v14, v246, v176
	ds_read_b128 v[186:189], v14
	ds_read_b128 v[190:193], v14 offset:4096
	ds_read_b128 v[194:197], v14 offset:8192
	ds_read_b128 v[202:205], v14 offset:12288
	v_add_u32_e32 v15, v246, v177
	ds_read_b128 v[206:209], v15
	ds_read_b128 v[210:213], v15 offset:4096
	v_sub_f32_e32 v0, v16, v181
	v_exp_f32_e32 v16, v0
	v_sub_f32_e32 v0, v17, v181
	v_exp_f32_e32 v17, v0
	v_sub_f32_e32 v0, v18, v181
	v_exp_f32_e32 v18, v0
	v_sub_f32_e32 v0, v19, v181
	v_exp_f32_e32 v19, v0
	v_sub_f32_e32 v2, v20, v181
	v_add_f32_e32 v0, 0, v16
	v_exp_f32_e32 v20, v2
	v_sub_f32_e32 v2, v21, v181
	v_add_f32_e32 v0, v17, v0
	v_exp_f32_e32 v21, v2
	v_sub_f32_e32 v2, v22, v181
	v_add_f32_e32 v0, v18, v0
	v_exp_f32_e32 v22, v2
	v_sub_f32_e32 v2, v23, v181
	v_add_f32_e32 v0, v19, v0
	v_exp_f32_e32 v23, v2
	v_sub_f32_e32 v2, v24, v181
	v_add_f32_e32 v0, v20, v0
	v_exp_f32_e32 v24, v2
	v_sub_f32_e32 v2, v25, v181
	v_add_f32_e32 v0, v21, v0
	v_exp_f32_e32 v25, v2
	v_sub_f32_e32 v2, v26, v181
	v_add_f32_e32 v0, v22, v0
	v_exp_f32_e32 v26, v2
	v_sub_f32_e32 v2, v27, v181
	v_add_f32_e32 v0, v23, v0
	v_exp_f32_e32 v27, v2
	v_sub_f32_e32 v2, v28, v181
	v_add_f32_e32 v0, v24, v0
	v_exp_f32_e32 v28, v2
	v_sub_f32_e32 v2, v29, v181
	v_add_f32_e32 v0, v25, v0
	v_exp_f32_e32 v29, v2
	v_sub_f32_e32 v2, v30, v181
	v_add_f32_e32 v0, v26, v0
	v_exp_f32_e32 v30, v2
	v_sub_f32_e32 v2, v31, v181
	v_add_f32_e32 v0, v27, v0
	v_exp_f32_e32 v31, v2
	v_sub_f32_e32 v2, v32, v181
	v_add_f32_e32 v0, v28, v0
	v_exp_f32_e32 v32, v2
	v_sub_f32_e32 v2, v33, v181
	v_add_f32_e32 v0, v29, v0
	v_exp_f32_e32 v33, v2
	v_sub_f32_e32 v2, v34, v181
	v_add_f32_e32 v0, v30, v0
	v_exp_f32_e32 v34, v2
	v_sub_f32_e32 v2, v35, v181
	v_add_f32_e32 v0, v31, v0
	v_exp_f32_e32 v35, v2
	v_sub_f32_e32 v2, v36, v181
	v_add_f32_e32 v0, v32, v0
	v_exp_f32_e32 v36, v2
	v_sub_f32_e32 v2, v37, v181
	v_add_f32_e32 v0, v33, v0
	v_exp_f32_e32 v37, v2
	v_sub_f32_e32 v2, v38, v181
	v_add_f32_e32 v0, v34, v0
	v_exp_f32_e32 v38, v2
	v_sub_f32_e32 v2, v39, v181
	v_add_f32_e32 v0, v35, v0
	v_exp_f32_e32 v39, v2
	v_sub_f32_e32 v2, v40, v181
	v_add_f32_e32 v0, v36, v0
	v_exp_f32_e32 v40, v2
	v_sub_f32_e32 v2, v41, v181
	v_add_f32_e32 v0, v37, v0
	v_exp_f32_e32 v41, v2
	v_sub_f32_e32 v2, v42, v181
	v_add_f32_e32 v0, v38, v0
	v_exp_f32_e32 v42, v2
	v_sub_f32_e32 v2, v43, v181
	v_add_f32_e32 v0, v39, v0
	v_exp_f32_e32 v43, v2
	v_sub_f32_e32 v2, v44, v181
	v_add_f32_e32 v0, v40, v0
	v_exp_f32_e32 v44, v2
	v_sub_f32_e32 v2, v45, v181
	v_add_f32_e32 v0, v41, v0
	v_exp_f32_e32 v45, v2
	v_sub_f32_e32 v2, v46, v181
	v_add_f32_e32 v0, v42, v0
	v_exp_f32_e32 v46, v2
	v_sub_f32_e32 v2, v47, v181
	v_add_f32_e32 v0, v43, v0
	v_exp_f32_e32 v47, v2
	v_add_f32_e32 v0, v44, v0
	v_add_f32_e32 v0, v45, v0
	v_add_f32_e32 v0, v46, v0
	v_add_f32_e32 v0, v47, v0
	v_add_f32_e32 v180, v180, v0
	v_cvt_pk_bf16_f32 v2, v16, v17
	v_cvt_pk_bf16_f32 v3, v18, v19
	v_cvt_pk_bf16_f32 v4, v20, v21
	v_cvt_pk_bf16_f32 v5, v22, v23
	v_cvt_pk_bf16_f32 v6, v24, v25
	v_cvt_pk_bf16_f32 v7, v26, v27
	v_cvt_pk_bf16_f32 v8, v28, v29
	v_cvt_pk_bf16_f32 v9, v30, v31
	v_cvt_pk_bf16_f32 v10, v32, v33
	v_cvt_pk_bf16_f32 v11, v34, v35
	v_cvt_pk_bf16_f32 v12, v36, v37
	v_cvt_pk_bf16_f32 v13, v38, v39
	v_cvt_pk_bf16_f32 v182, v40, v41
	v_cvt_pk_bf16_f32 v183, v42, v43
	v_cvt_pk_bf16_f32 v184, v44, v45
	v_cvt_pk_bf16_f32 v185, v46, v47
	v_add_u32_e32 v14, v246, v178
	v_add_u32_e32 v0, v246, v179
	s_waitcnt lgkmcnt(5)
	s_setprio 2
	v_mfma_f32_32x32x16_bf16 v[96:111], v[186:189], v[2:5], v[96:111]
	ds_read_b128 v[186:189], v15 offset:8192
	s_waitcnt lgkmcnt(5)
	v_mfma_f32_32x32x16_bf16 v[80:95], v[190:193], v[2:5], v[80:95]
	ds_read_b128 v[190:193], v15 offset:12288
	s_waitcnt lgkmcnt(5)
	v_mfma_f32_32x32x16_bf16 v[64:79], v[194:197], v[2:5], v[64:79]
	ds_read_b128 v[194:197], v14
	s_waitcnt lgkmcnt(5)
	v_mfma_f32_32x32x16_bf16 v[48:63], v[202:205], v[2:5], v[48:63]
	ds_read_b128 v[2:5], v14 offset:4096
	s_waitcnt lgkmcnt(5)
	v_mfma_f32_32x32x16_bf16 v[96:111], v[206:209], v[6:9], v[96:111]
	ds_read_b128 v[202:205], v14 offset:8192
	s_waitcnt lgkmcnt(5)
	v_mfma_f32_32x32x16_bf16 v[80:95], v[210:213], v[6:9], v[80:95]
	ds_read_b128 v[206:209], v14 offset:12288
	s_waitcnt lgkmcnt(5)
	v_mfma_f32_32x32x16_bf16 v[64:79], v[186:189], v[6:9], v[64:79]
	ds_read_b128 v[186:189], v0
	s_waitcnt lgkmcnt(5)
	v_mfma_f32_32x32x16_bf16 v[48:63], v[190:193], v[6:9], v[48:63]
	ds_read_b128 v[6:9], v0 offset:4096
	s_waitcnt lgkmcnt(5)
	v_mfma_f32_32x32x16_bf16 v[96:111], v[194:197], v[10:13], v[96:111]
	ds_read_b128 v[190:193], v0 offset:8192
	s_waitcnt lgkmcnt(5)
	v_mfma_f32_32x32x16_bf16 v[80:95], v[2:5], v[10:13], v[80:95]
	ds_read_b128 v[2:5], v0 offset:12288
	s_waitcnt lgkmcnt(5)
	v_mfma_f32_32x32x16_bf16 v[64:79], v[202:205], v[10:13], v[64:79]
	s_waitcnt lgkmcnt(4)
	v_mfma_f32_32x32x16_bf16 v[48:63], v[206:209], v[10:13], v[48:63]
	s_waitcnt lgkmcnt(3)
	v_mfma_f32_32x32x16_bf16 v[96:111], v[186:189], v[182:185], v[96:111]
	s_waitcnt lgkmcnt(2)
	v_mfma_f32_32x32x16_bf16 v[80:95], v[6:9], v[182:185], v[80:95]
	s_waitcnt lgkmcnt(1)
	v_mfma_f32_32x32x16_bf16 v[64:79], v[190:193], v[182:185], v[64:79]
	s_waitcnt lgkmcnt(0)
	v_mfma_f32_32x32x16_bf16 v[48:63], v[2:5], v[182:185], v[48:63]
	s_setprio 1
; #define LAS __attribute__((address_space(3)))
; template <bool MLA, bool grpB>
; __device__ __forceinline__ void attn_unit_g(LAS unsigned char* lds, const AttnPtrs& P, int b, int h, int qblk) {
;     ...
;     auto qk = [&](int koff) {
;         if (MLA) {
;         } else {
; #pragma unroll
;             for (int blk = 0; blk < 2; ++blk)
; #pragma unroll
;                 for (int g = 0; g < 4; ++g) { const f32x4 c4 = *(const LAS f32x4*)(lds + koff + KTILE + (32 * blk + 16 * hi + 4 * g) * 4);
; #pragma unroll
;                     for (int e = 0; e < 4; ++e) sc[blk][4 * g + e] = c4[e]; }
;         }
;         const LAS unsigned char* ka = lds + koff + karow;
;         bf16x8 a[PFD];
;         auto ld = [&](int i) -> bf16x8 {
;             const int d0 = i >> 1, blk = i & 1, seg = 2 * d0;
;             int so;
;             if (MLA) so = (((seg + hi) & 24) | (((seg + hi) ^ kswz) & 7)) * 16; else so = ((seg + hi) ^ kswz) * 16;
;             return *(const LAS bf16x8*)(ka + blk * 32 * KROW + so);
;         };
; #pragma unroll
;         for (int i = 0; i < PFD; ++i) a[i] = ld(i);
; #pragma unroll
;         for (int i = 0; i < 2 * ND0; ++i) {
;             const f32x16 zc = {0.f, 0.f, 0.f, 0.f, 0.f, 0.f, 0.f, 0.f, 0.f, 0.f, 0.f, 0.f, 0.f, 0.f, 0.f, 0.f};
;             sc[i & 1] = __builtin_amdgcn_mfma_f32_32x32x16_bf16(a[i % PFD], qf[i >> 1], (MLA && i < 2) ? zc : sc[i & 1], 0, 0, 0);
;             if (i + PFD < 2 * ND0) a[i % PFD] = ld(i + PFD);
;         }
;         __builtin_amdgcn_sched_group_barrier(0x100, PFD, 0);
; #pragma unroll
;         for (int i = 0; i < 2 * ND0; ++i) { __builtin_amdgcn_sched_group_barrier(0x008, 1, 0); __builtin_amdgcn_sched_group_barrier(0x100, 1, 0); }
;         __builtin_amdgcn_sched_barrier(0);
;     };
.LBB0_1269:
	s_cmpk_eq_i32 s64, 0xff40
	s_cselect_b64 s[8:9], -1, 0
	s_cmp_gt_i32 s48, s97
	s_cselect_b64 s[10:11], -1, 0
	s_or_b64 s[8:9], s[8:9], s[10:11]
	s_and_b64 vcc, exec, s[8:9]
	s_cbranch_vccnz .LBB0_1273
	s_add_i32 s8, s56, 0
	v_add_u32_e32 v0, s8, v161
	ds_read_b128 v[16:19], v0 offset:16384
	ds_read_b128 v[20:23], v0 offset:16400
	ds_read_b128 v[24:27], v0 offset:16416
	ds_read_b128 v[28:31], v0 offset:16432
	ds_read_b128 v[32:35], v0 offset:16512
	ds_read_b128 v[36:39], v0 offset:16528
	ds_read_b128 v[40:43], v0 offset:16544
	ds_read_b128 v[44:47], v0 offset:16560
	v_add_u32_e32 v0, s8, v147
	v_add_u32_e32 v6, v0, v162
	v_add_u32_e32 v7, v0, v163
	v_add_u32_e32 v8, v0, v164
	v_add_u32_e32 v9, v0, v165
	v_add_u32_e32 v10, v0, v166
	v_add_u32_e32 v11, v0, v167
	v_add_u32_e32 v12, v0, v168
	v_add_u32_e32 v0, v0, v169
	ds_read_b128 v[182:185], v6 offset:8192
	ds_read_b128 v[186:189], v7 offset:8192
	ds_read_b128 v[190:193], v8 offset:8192
	ds_read_b128 v[194:197], v9 offset:8192
	ds_read_b128 v[202:205], v10 offset:8192
	ds_read_b128 v[210:213], v11 offset:8192
	s_waitcnt lgkmcnt(5)
	s_setprio 2
	v_mfma_f32_32x32x16_bf16 v[32:47], v[182:185], v[136:139], v[32:47]
	ds_read_b128 v[182:185], v12 offset:8192
	s_waitcnt lgkmcnt(5)
	v_mfma_f32_32x32x16_bf16 v[32:47], v[186:189], v[112:115], v[32:47]
	ds_read_b128 v[186:189], v0 offset:8192
	s_waitcnt lgkmcnt(5)
	v_mfma_f32_32x32x16_bf16 v[32:47], v[190:193], v[116:119], v[32:47]
	ds_read_b128 v[190:193], v6
	s_waitcnt lgkmcnt(5)
	v_mfma_f32_32x32x16_bf16 v[32:47], v[194:197], v[120:123], v[32:47]
	ds_read_b128 v[194:197], v7
	s_waitcnt lgkmcnt(5)
	v_mfma_f32_32x32x16_bf16 v[32:47], v[202:205], v[124:127], v[32:47]
	ds_read_b128 v[202:205], v8
	s_waitcnt lgkmcnt(5)
	v_mfma_f32_32x32x16_bf16 v[32:47], v[210:213], v[128:131], v[32:47]
	ds_read_b128 v[210:213], v9
	s_waitcnt lgkmcnt(5)
	v_mfma_f32_32x32x16_bf16 v[32:47], v[182:185], v[132:135], v[32:47]
	ds_read_b128 v[182:185], v10
	s_waitcnt lgkmcnt(5)
	v_mfma_f32_32x32x16_bf16 v[32:47], v[186:189], v[140:143], v[32:47]
	ds_read_b128 v[186:189], v11
	s_waitcnt lgkmcnt(5)
	v_mfma_f32_32x32x16_bf16 v[16:31], v[190:193], v[136:139], v[16:31]
	ds_read_b128 v[190:193], v12
	s_waitcnt lgkmcnt(5)
	v_mfma_f32_32x32x16_bf16 v[16:31], v[194:197], v[112:115], v[16:31]
	ds_read_b128 v[194:197], v0
	s_waitcnt lgkmcnt(5)
	v_mfma_f32_32x32x16_bf16 v[16:31], v[202:205], v[116:119], v[16:31]
	s_waitcnt lgkmcnt(4)
	v_mfma_f32_32x32x16_bf16 v[16:31], v[210:213], v[120:123], v[16:31]
	s_waitcnt lgkmcnt(3)
	v_mfma_f32_32x32x16_bf16 v[16:31], v[182:185], v[124:127], v[16:31]
	s_waitcnt lgkmcnt(2)
	v_mfma_f32_32x32x16_bf16 v[16:31], v[186:189], v[128:131], v[16:31]
	s_waitcnt lgkmcnt(1)
	v_mfma_f32_32x32x16_bf16 v[16:31], v[190:193], v[132:135], v[16:31]
	s_waitcnt lgkmcnt(0)
	v_mfma_f32_32x32x16_bf16 v[16:31], v[194:197], v[140:143], v[16:31]
	s_setprio 1
	s_mov_b64 s[8:9], -1
	s_and_b64 vcc, exec, s[74:75]
	s_cbranch_vccnz .LBB0_1274

; #define LAS __attribute__((address_space(3)))
; template <bool MLA, bool grpB>
; __device__ __forceinline__ void attn_unit_g(LAS unsigned char* lds, const AttnPtrs& P, int b, int h, int qblk) {
;     ...
;     auto qk = [&](int koff) {
;         if (MLA) {
;         } else {
; #pragma unroll
;             for (int blk = 0; blk < 2; ++blk)
; #pragma unroll
;                 for (int g = 0; g < 4; ++g) { const f32x4 c4 = *(const LAS f32x4*)(lds + koff + KTILE + (32 * blk + 16 * hi + 4 * g) * 4);
; #pragma unroll
;                     for (int e = 0; e < 4; ++e) sc[blk][4 * g + e] = c4[e]; }
;         }
;         const LAS unsigned char* ka = lds + koff + karow;
;         bf16x8 a[PFD];
;         auto ld = [&](int i) -> bf16x8 {
;             const int d0 = i >> 1, blk = i & 1, seg = 2 * d0;
;             int so;
;             if (MLA) so = (((seg + hi) & 24) | (((seg + hi) ^ kswz) & 7)) * 16; else so = ((seg + hi) ^ kswz) * 16;
;             return *(const LAS bf16x8*)(ka + blk * 32 * KROW + so);
;         };
; #pragma unroll
;         for (int i = 0; i < PFD; ++i) a[i] = ld(i);
; #pragma unroll
;         for (int i = 0; i < 2 * ND0; ++i) {
;             const f32x16 zc = {0.f, 0.f, 0.f, 0.f, 0.f, 0.f, 0.f, 0.f, 0.f, 0.f, 0.f, 0.f, 0.f, 0.f, 0.f, 0.f};
;             sc[i & 1] = __builtin_amdgcn_mfma_f32_32x32x16_bf16(a[i % PFD], qf[i >> 1], (MLA && i < 2) ? zc : sc[i & 1], 0, 0, 0);
;             if (i + PFD < 2 * ND0) a[i % PFD] = ld(i + PFD);
;         }
;         __builtin_amdgcn_sched_group_barrier(0x100, PFD, 0);
; #pragma unroll
;         for (int i = 0; i < 2 * ND0; ++i) { __builtin_amdgcn_sched_group_barrier(0x008, 1, 0); __builtin_amdgcn_sched_group_barrier(0x100, 1, 0); }
;         __builtin_amdgcn_sched_barrier(0);
;     };
;     float mref = -1e30f;
;     auto sm = [&](int j) {
;         if (j >= my_last) {
;             if (MLA) { if (j > my_last) {
; #pragma unroll
;                 for (int r = 0; r < 16; ++r) { sc[0][r] = -2e30f; sc[1][r] = -2e30f; } } }
;             else { const int qpos = q0 + r32;
; #pragma unroll
;                 for (int blk = 0; blk < 2; ++blk)
; #pragma unroll
;                     for (int r = 0; r < 16; ++r) { const int key = 64 * j + 32 * blk + 16 * hi + r; if (key > qpos) sc[blk][r] = -2e30f; } }
.LBB0_1313:
	s_add_i32 s8, s51, 0
	v_add_u32_e32 v0, s8, v161
	ds_read_b128 v[96:99], v0 offset:16384
	ds_read_b128 v[100:103], v0 offset:16400
	ds_read_b128 v[104:107], v0 offset:16416
	ds_read_b128 v[108:111], v0 offset:16432
	ds_read_b128 v[80:83], v0 offset:16512
	ds_read_b128 v[84:87], v0 offset:16528
	ds_read_b128 v[88:91], v0 offset:16544
	ds_read_b128 v[92:95], v0 offset:16560
	v_add_u32_e32 v0, s8, v147
	v_add_u32_e32 v6, v0, v162
	v_add_u32_e32 v7, v0, v163
	v_add_u32_e32 v8, v0, v164
	v_add_u32_e32 v9, v0, v165
	v_add_u32_e32 v10, v0, v166
	v_add_u32_e32 v11, v0, v167
	v_add_u32_e32 v12, v0, v168
	v_add_u32_e32 v0, v0, v169
	ds_read_b128 v[182:185], v6 offset:8192
	ds_read_b128 v[186:189], v7 offset:8192
	ds_read_b128 v[190:193], v8 offset:8192
	ds_read_b128 v[194:197], v9 offset:8192
	ds_read_b128 v[202:205], v10 offset:8192
	ds_read_b128 v[210:213], v11 offset:8192
	s_waitcnt lgkmcnt(5)
	s_setprio 2
	v_mfma_f32_32x32x16_bf16 v[80:95], v[182:185], v[136:139], v[80:95]
	ds_read_b128 v[182:185], v12 offset:8192
	s_waitcnt lgkmcnt(5)
	v_mfma_f32_32x32x16_bf16 v[80:95], v[186:189], v[112:115], v[80:95]
	ds_read_b128 v[186:189], v0 offset:8192
	s_waitcnt lgkmcnt(5)
	v_mfma_f32_32x32x16_bf16 v[80:95], v[190:193], v[116:119], v[80:95]
	ds_read_b128 v[190:193], v6
	s_waitcnt lgkmcnt(5)
	v_mfma_f32_32x32x16_bf16 v[80:95], v[194:197], v[120:123], v[80:95]
	ds_read_b128 v[194:197], v7
	s_waitcnt lgkmcnt(5)
	v_mfma_f32_32x32x16_bf16 v[80:95], v[202:205], v[124:127], v[80:95]
	ds_read_b128 v[202:205], v8
	s_waitcnt lgkmcnt(5)
	v_mfma_f32_32x32x16_bf16 v[80:95], v[210:213], v[128:131], v[80:95]
	ds_read_b128 v[210:213], v9
	s_waitcnt lgkmcnt(5)
	v_mfma_f32_32x32x16_bf16 v[80:95], v[182:185], v[132:135], v[80:95]
	ds_read_b128 v[182:185], v10
	s_waitcnt lgkmcnt(5)
	v_mfma_f32_32x32x16_bf16 v[80:95], v[186:189], v[140:143], v[80:95]
	ds_read_b128 v[186:189], v11
	s_waitcnt lgkmcnt(5)
	v_mfma_f32_32x32x16_bf16 v[96:111], v[190:193], v[136:139], v[96:111]
	ds_read_b128 v[190:193], v12
	s_waitcnt lgkmcnt(5)
	v_mfma_f32_32x32x16_bf16 v[96:111], v[194:197], v[112:115], v[96:111]
	ds_read_b128 v[194:197], v0
	s_waitcnt lgkmcnt(5)
	v_mfma_f32_32x32x16_bf16 v[96:111], v[202:205], v[116:119], v[96:111]
	s_waitcnt lgkmcnt(4)
	v_mfma_f32_32x32x16_bf16 v[96:111], v[210:213], v[120:123], v[96:111]
	s_waitcnt lgkmcnt(3)
	v_mfma_f32_32x32x16_bf16 v[96:111], v[182:185], v[124:127], v[96:111]
	s_waitcnt lgkmcnt(2)
	v_mfma_f32_32x32x16_bf16 v[96:111], v[186:189], v[128:131], v[96:111]
	s_waitcnt lgkmcnt(1)
	v_mfma_f32_32x32x16_bf16 v[96:111], v[190:193], v[132:135], v[96:111]
	s_waitcnt lgkmcnt(0)
	v_mfma_f32_32x32x16_bf16 v[96:111], v[194:197], v[140:143], v[96:111]
	s_setprio 0
	s_cmp_lt_u32 s10, s54
	s_cbranch_scc1 .LBB0_1317
	v_add_u32_e32 v0, s64, v146
	v_add_u32_e32 v2, 0xc0, v0
	v_cmp_le_i32_e32 vcc, v2, v173
	v_cmp_lt_i32_e64 s[8:9], v2, v173
	v_add_u32_e32 v2, 0xc2, v0
	v_cmp_le_i32_e64 s[10:11], v2, v173
	v_add_u32_e32 v2, 0xc3, v0
	v_cmp_le_i32_e64 s[12:13], v2, v173
	v_add_u32_e32 v2, 0xc4, v0
	v_cmp_le_i32_e64 s[14:15], v2, v173
	v_add_u32_e32 v2, 0xc5, v0
	v_cmp_le_i32_e64 s[16:17], v2, v173
	v_add_u32_e32 v2, 0xc6, v0
	v_cmp_le_i32_e64 s[18:19], v2, v173
	v_add_u32_e32 v2, 0xc7, v0
	v_cmp_le_i32_e64 s[20:21], v2, v173
	v_add_u32_e32 v2, 0xc8, v0
	v_cmp_le_i32_e64 s[22:23], v2, v173
	v_add_u32_e32 v2, 0xc9, v0
	v_cmp_le_i32_e64 s[24:25], v2, v173
	v_add_u32_e32 v2, 0xca, v0
	v_cmp_le_i32_e64 s[26:27], v2, v173
	v_add_u32_e32 v2, 0xcb, v0
	v_cmp_le_i32_e64 s[28:29], v2, v173
	v_add_u32_e32 v2, 0xcc, v0
	v_cmp_le_i32_e64 s[30:31], v2, v173
	v_add_u32_e32 v2, 0xcd, v0
	v_cmp_le_i32_e64 s[34:35], v2, v173
	v_add_u32_e32 v2, 0xce, v0
	v_cmp_le_i32_e64 s[36:37], v2, v173
	v_add_u32_e32 v2, 0xcf, v0
	v_cmp_le_i32_e64 s[38:39], v2, v173
	v_add_u32_e32 v2, 0xe0, v0
	v_cmp_le_i32_e64 s[42:43], v2, v173
	v_add_u32_e32 v2, 0xe1, v0
	s_nop 0
	v_cndmask_b32_e64 v80, v159, v80, s[42:43]
	v_cmp_le_i32_e64 s[42:43], v2, v173
	v_add_u32_e32 v2, 0xe2, v0
	s_nop 0
	v_cndmask_b32_e64 v81, v159, v81, s[42:43]
	v_cmp_le_i32_e64 s[42:43], v2, v173
	v_add_u32_e32 v2, 0xe3, v0
	s_nop 0
	v_cndmask_b32_e64 v82, v159, v82, s[42:43]
	v_cmp_le_i32_e64 s[42:43], v2, v173
	v_add_u32_e32 v2, 0xe4, v0
	s_nop 0
	v_cndmask_b32_e64 v83, v159, v83, s[42:43]
	v_cmp_le_i32_e64 s[42:43], v2, v173
	v_add_u32_e32 v2, 0xe5, v0
	s_nop 0
	v_cndmask_b32_e64 v84, v159, v84, s[42:43]
	v_cmp_le_i32_e64 s[42:43], v2, v173
	v_add_u32_e32 v2, 0xe6, v0
	s_nop 0
	v_cndmask_b32_e64 v85, v159, v85, s[42:43]
	v_cmp_le_i32_e64 s[42:43], v2, v173
	v_add_u32_e32 v2, 0xe7, v0
	s_nop 0
	v_cndmask_b32_e64 v86, v159, v86, s[42:43]
	v_cmp_le_i32_e64 s[42:43], v2, v173
	v_add_u32_e32 v2, 0xe8, v0
	s_nop 0
	v_cndmask_b32_e64 v87, v159, v87, s[42:43]
	v_cmp_le_i32_e64 s[42:43], v2, v173
	v_add_u32_e32 v2, 0xe9, v0
	s_nop 0
	v_cndmask_b32_e64 v88, v159, v88, s[42:43]
	v_cmp_le_i32_e64 s[42:43], v2, v173
	v_add_u32_e32 v2, 0xea, v0
	s_nop 0
	v_cndmask_b32_e64 v89, v159, v89, s[42:43]
	v_cmp_le_i32_e64 s[42:43], v2, v173
	v_add_u32_e32 v2, 0xeb, v0
	s_nop 0
	v_cndmask_b32_e64 v90, v159, v90, s[42:43]
	v_cmp_le_i32_e64 s[42:43], v2, v173
	v_add_u32_e32 v2, 0xec, v0
	s_nop 0
	v_cndmask_b32_e64 v91, v159, v91, s[42:43]
	v_cmp_le_i32_e64 s[42:43], v2, v173
	v_add_u32_e32 v2, 0xed, v0
	s_nop 0
	v_cndmask_b32_e64 v92, v159, v92, s[42:43]
	v_cmp_le_i32_e64 s[42:43], v2, v173
	v_add_u32_e32 v2, 0xee, v0
	v_add_u32_e32 v0, 0xef, v0
	v_cndmask_b32_e64 v93, v159, v93, s[42:43]
	v_cmp_le_i32_e64 s[42:43], v2, v173
	s_nop 1
	v_cndmask_b32_e64 v94, v159, v94, s[42:43]
	v_cmp_gt_i32_e64 s[42:43], v0, v173
	s_and_saveexec_b64 s[76:77], s[42:43]
	v_mov_b32_e32 v95, s87
	s_or_b64 exec, exec, s[76:77]
	v_cndmask_b32_e64 v97, v159, v97, s[8:9]
	v_cndmask_b32_e32 v96, v159, v96, vcc
	v_cndmask_b32_e64 v98, v159, v98, s[10:11]
	v_cndmask_b32_e64 v99, v159, v99, s[12:13]
	v_cndmask_b32_e64 v100, v159, v100, s[14:15]
	v_cndmask_b32_e64 v101, v159, v101, s[16:17]
	v_cndmask_b32_e64 v102, v159, v102, s[18:19]
	v_cndmask_b32_e64 v103, v159, v103, s[20:21]
	v_cndmask_b32_e64 v104, v159, v104, s[22:23]
	v_cndmask_b32_e64 v105, v159, v105, s[24:25]
	v_cndmask_b32_e64 v106, v159, v106, s[26:27]
	v_cndmask_b32_e64 v107, v159, v107, s[28:29]
	v_cndmask_b32_e64 v108, v159, v108, s[30:31]
	v_cndmask_b32_e64 v109, v159, v109, s[34:35]
	v_cndmask_b32_e64 v110, v159, v110, s[36:37]
	v_cndmask_b32_e64 v111, v159, v111, s[38:39]

; __device__ __forceinline__ unsigned cvt_pk_bf16(float lo, float hi) { unsigned r; asm volatile("v_cvt_pk_bf16_f32 %0, %1, %2" : "=v"(r) : "v"(lo), "v"(hi)); return r; }
; #define LAS __attribute__((address_space(3)))
; template <bool MLA, bool grpB>
; __device__ __forceinline__ void attn_unit_g(LAS unsigned char* lds, const AttnPtrs& P, int b, int h, int qblk) {
;     ...
;         float ps = 0.f;
; #pragma unroll
;         for (int blk = 0; blk < 2; ++blk)
; #pragma unroll
;             for (int r = 0; r < 16; ++r) { const float pv_ = __builtin_amdgcn_exp2f(sc[blk][r] - mref); sc[blk][r] = pv_; ps += pv_; }
;         lrun += ps;
; #pragma unroll
;         for (int blk = 0; blk < 2; ++blk)
; #pragma unroll
;             for (int ks = 0; ks < 2; ++ks) { u32x4 w;
;                 w.x = pg8::cvt_pk_bf16(sc[blk][8 * ks + 0], sc[blk][8 * ks + 1]); w.y = pg8::cvt_pk_bf16(sc[blk][8 * ks + 2], sc[blk][8 * ks + 3]);
;                 w.z = pg8::cvt_pk_bf16(sc[blk][8 * ks + 4], sc[blk][8 * ks + 5]); w.w = pg8::cvt_pk_bf16(sc[blk][8 * ks + 6], sc[blk][8 * ks + 7]);
;                 pb[blk][ks] = __builtin_bit_cast(bf16x8, w); }
;         __builtin_amdgcn_sched_barrier(0);
;     };
;     auto pv = [&](int voff) {
;         const LAS unsigned char* va = lds + varow + voff;
;         bf16x8 a[PFD];
;         auto ld = [&](int i) -> bf16x8 {
;             const int dvb = i & 3, bk = i >> 2, so = ((4 * (bk >> 1) + 2 * hi + (bk & 1)) ^ vswz) * 16;
;             return *(const LAS bf16x8*)(va + 32 * dvb * VROW + so);
;         };
; #pragma unroll
;         for (int i = 0; i < PFD; ++i) a[i] = ld(i);
; #pragma unroll
;         for (int i = 0; i < 16; ++i) {
;             o[i & 3] = __builtin_amdgcn_mfma_f32_32x32x16_bf16(a[i % PFD], pb[i >> 3][(i >> 2) & 1], o[i & 3], 0, 0, 0);
;             if (i + PFD < 16) a[i % PFD] = ld(i + PFD);
;         }
;         __builtin_amdgcn_sched_group_barrier(0x100, PFD, 0);
; #pragma unroll
;         for (int i = 0; i < 16; ++i) { __builtin_amdgcn_sched_group_barrier(0x008, 1, 0); __builtin_amdgcn_sched_group_barrier(0x100, 1, 0); }
;         __builtin_amdgcn_sched_barrier(0);
.LBB0_1319:
	v_sub_f32_e32 v0, v96, v181
	v_exp_f32_e32 v0, v0
	v_sub_f32_e32 v2, v97, v181
	v_exp_f32_e32 v2, v2
	v_sub_f32_e32 v3, v98, v181
	v_exp_f32_e32 v3, v3
	v_sub_f32_e32 v4, v99, v181
	v_exp_f32_e32 v4, v4
	v_sub_f32_e32 v6, v100, v181
	v_add_f32_e32 v5, 0, v0
	v_exp_f32_e32 v6, v6
	v_sub_f32_e32 v7, v101, v181
	v_add_f32_e32 v5, v2, v5
	v_exp_f32_e32 v7, v7
	v_sub_f32_e32 v8, v102, v181
	v_add_f32_e32 v5, v3, v5
	v_exp_f32_e32 v8, v8
	v_sub_f32_e32 v9, v103, v181
	v_add_f32_e32 v5, v4, v5
	v_exp_f32_e32 v9, v9
	v_sub_f32_e32 v10, v104, v181
	v_add_f32_e32 v5, v6, v5
	v_exp_f32_e32 v10, v10
	v_sub_f32_e32 v11, v105, v181
	v_add_f32_e32 v5, v7, v5
	v_exp_f32_e32 v11, v11
	v_sub_f32_e32 v12, v106, v181
	v_add_f32_e32 v5, v8, v5
	v_exp_f32_e32 v12, v12
	v_sub_f32_e32 v13, v107, v181
	v_add_f32_e32 v5, v9, v5
	v_exp_f32_e32 v13, v13
	v_sub_f32_e32 v14, v108, v181
	v_add_f32_e32 v5, v10, v5
	v_exp_f32_e32 v14, v14
	v_sub_f32_e32 v15, v109, v181
	v_add_f32_e32 v5, v11, v5
	v_exp_f32_e32 v15, v15
	v_sub_f32_e32 v96, v110, v181
	v_add_f32_e32 v5, v12, v5
	v_exp_f32_e32 v96, v96
	v_sub_f32_e32 v97, v111, v181
	v_add_f32_e32 v5, v13, v5
	v_exp_f32_e32 v97, v97
	v_sub_f32_e32 v80, v80, v181
	v_add_f32_e32 v5, v14, v5
	v_exp_f32_e32 v80, v80
	v_sub_f32_e32 v81, v81, v181
	v_add_f32_e32 v5, v15, v5
	v_exp_f32_e32 v81, v81
	v_sub_f32_e32 v82, v82, v181
	v_add_f32_e32 v5, v96, v5
	v_exp_f32_e32 v82, v82
	v_sub_f32_e32 v83, v83, v181
	v_add_f32_e32 v5, v97, v5
	v_exp_f32_e32 v83, v83
	v_sub_f32_e32 v84, v84, v181
	v_add_f32_e32 v5, v80, v5
	v_exp_f32_e32 v84, v84
	v_sub_f32_e32 v85, v85, v181
	v_add_f32_e32 v5, v81, v5
	v_exp_f32_e32 v85, v85
	v_sub_f32_e32 v86, v86, v181
	v_add_f32_e32 v5, v82, v5
	v_exp_f32_e32 v86, v86
	v_sub_f32_e32 v87, v87, v181
	v_add_f32_e32 v5, v83, v5
	v_exp_f32_e32 v87, v87
	v_sub_f32_e32 v88, v88, v181
	v_add_f32_e32 v5, v84, v5
	v_exp_f32_e32 v88, v88
	v_sub_f32_e32 v89, v89, v181
	v_add_f32_e32 v5, v85, v5
	v_exp_f32_e32 v89, v89
	v_sub_f32_e32 v90, v90, v181
	v_add_f32_e32 v5, v86, v5
	v_exp_f32_e32 v90, v90
	v_sub_f32_e32 v91, v91, v181
	v_add_f32_e32 v5, v87, v5
	v_exp_f32_e32 v91, v91
	v_sub_f32_e32 v92, v92, v181
	v_add_f32_e32 v5, v88, v5
	v_exp_f32_e32 v92, v92
	v_sub_f32_e32 v93, v93, v181
	v_add_f32_e32 v5, v89, v5
	v_exp_f32_e32 v93, v93
	v_sub_f32_e32 v94, v94, v181
	v_add_f32_e32 v5, v90, v5
	v_exp_f32_e32 v94, v94
	v_sub_f32_e32 v95, v95, v181
	v_add_f32_e32 v5, v91, v5
	v_exp_f32_e32 v95, v95
	v_add_f32_e32 v5, v92, v5
	v_add_f32_e32 v5, v93, v5
	v_add_f32_e32 v5, v94, v5
	v_add_f32_e32 v5, v95, v5
	v_add_f32_e32 v180, v180, v5
	v_cvt_pk_bf16_f32 v2, v0, v2
	v_cvt_pk_bf16_f32 v3, v3, v4
	v_cvt_pk_bf16_f32 v4, v6, v7
	v_cvt_pk_bf16_f32 v5, v8, v9
	v_cvt_pk_bf16_f32 v6, v10, v11
	v_cvt_pk_bf16_f32 v7, v12, v13
	v_cvt_pk_bf16_f32 v8, v14, v15
	v_cvt_pk_bf16_f32 v9, v96, v97
	v_cvt_pk_bf16_f32 v10, v80, v81
	v_cvt_pk_bf16_f32 v11, v82, v83
	v_cvt_pk_bf16_f32 v12, v84, v85
	v_cvt_pk_bf16_f32 v13, v86, v87
	v_cvt_pk_bf16_f32 v80, v88, v89
	v_cvt_pk_bf16_f32 v81, v90, v91
	v_cvt_pk_bf16_f32 v82, v92, v93
	v_cvt_pk_bf16_f32 v83, v94, v95
	v_add_u32_e32 v0, s41, v175
	v_add_u32_e32 v14, v0, v176
	ds_read_b128 v[84:87], v14
	ds_read_b128 v[88:91], v14 offset:4096
	ds_read_b128 v[92:95], v14 offset:8192
	ds_read_b128 v[96:99], v14 offset:12288
	v_add_u32_e32 v15, v0, v177
	ds_read_b128 v[100:103], v15
	ds_read_b128 v[104:107], v15 offset:4096
	v_add_u32_e32 v14, v0, v178
	v_add_u32_e32 v0, v0, v179
	s_waitcnt lgkmcnt(5)
	s_setprio 2
	v_mfma_f32_32x32x16_bf16 v[64:79], v[84:87], v[2:5], v[64:79]
	ds_read_b128 v[84:87], v15 offset:8192
	s_waitcnt lgkmcnt(5)
	v_mfma_f32_32x32x16_bf16 v[48:63], v[88:91], v[2:5], v[48:63]
	ds_read_b128 v[88:91], v15 offset:12288
	s_waitcnt lgkmcnt(5)
	v_mfma_f32_32x32x16_bf16 v[32:47], v[92:95], v[2:5], v[32:47]
	ds_read_b128 v[92:95], v14
	s_waitcnt lgkmcnt(5)
	v_mfma_f32_32x32x16_bf16 v[16:31], v[96:99], v[2:5], v[16:31]
	ds_read_b128 v[2:5], v14 offset:4096
	s_waitcnt lgkmcnt(5)
	v_mfma_f32_32x32x16_bf16 v[64:79], v[100:103], v[6:9], v[64:79]
	ds_read_b128 v[96:99], v14 offset:8192
	s_waitcnt lgkmcnt(5)
	v_mfma_f32_32x32x16_bf16 v[48:63], v[104:107], v[6:9], v[48:63]
	ds_read_b128 v[100:103], v14 offset:12288
	s_waitcnt lgkmcnt(5)
	v_mfma_f32_32x32x16_bf16 v[32:47], v[84:87], v[6:9], v[32:47]
	ds_read_b128 v[84:87], v0
	s_waitcnt lgkmcnt(5)
	v_mfma_f32_32x32x16_bf16 v[16:31], v[88:91], v[6:9], v[16:31]
	ds_read_b128 v[6:9], v0 offset:4096
	s_waitcnt lgkmcnt(5)
	v_mfma_f32_32x32x16_bf16 v[64:79], v[92:95], v[10:13], v[64:79]
	ds_read_b128 v[88:91], v0 offset:8192
	s_waitcnt lgkmcnt(5)
	v_mfma_f32_32x32x16_bf16 v[48:63], v[2:5], v[10:13], v[48:63]
	ds_read_b128 v[2:5], v0 offset:12288
	s_waitcnt lgkmcnt(5)
	v_mfma_f32_32x32x16_bf16 v[32:47], v[96:99], v[10:13], v[32:47]
	s_waitcnt lgkmcnt(4)
	v_mfma_f32_32x32x16_bf16 v[16:31], v[100:103], v[10:13], v[16:31]
	s_waitcnt lgkmcnt(3)
	v_mfma_f32_32x32x16_bf16 v[64:79], v[84:87], v[80:83], v[64:79]
	s_waitcnt lgkmcnt(2)
	v_mfma_f32_32x32x16_bf16 v[48:63], v[6:9], v[80:83], v[48:63]
	s_waitcnt lgkmcnt(1)
	v_mfma_f32_32x32x16_bf16 v[32:47], v[88:91], v[80:83], v[32:47]
	s_waitcnt lgkmcnt(0)
	v_mfma_f32_32x32x16_bf16 v[16:31], v[2:5], v[80:83], v[16:31]
	s_setprio 0
	s_mov_b64 s[8:9], -1
	s_and_b64 vcc, exec, s[74:75]
	s_cbranch_vccnz .LBB0_1325

; __device__ __forceinline__ void xcd_barrier(const XcdBarrier& b) {
;     asm volatile("s_waitcnt vmcnt(0)" ::: "memory");
;     __syncthreads();
;     if (threadIdx.x == 0) {
;         unsigned* bar = b.bar;
;         __builtin_amdgcn_s_waitcnt(0);
;         unsigned nloc = b.st[0], nx = b.st[1];
;         if (nloc == 0u) { xcd_barrier_complete(bar, b.x, nloc, nx); b.st[0] = nloc; b.st[1] = nx; }
.LBB0_1337:
	s_setprio 0
	s_waitcnt vmcnt(0)
	s_waitcnt vmcnt(0) lgkmcnt(0)
	s_barrier
	s_and_saveexec_b64 s[4:5], s[86:87]
	s_xor_b64 s[4:5], exec, s[4:5]
	s_cbranch_execz .LBB0_1390
	s_add_i32 s3, 0, 0x26c00
	v_mov_b32_e32 v0, s3
	s_waitcnt vmcnt(0) expcnt(0) lgkmcnt(0)
	ds_read_b32 v2, v0
	s_add_i32 s3, 0, 0x26c04
	v_mov_b32_e32 v0, s3
	ds_read_b32 v0, v0
	s_waitcnt lgkmcnt(1)
	v_cmp_ne_u32_e32 vcc, 0, v2
	s_cbranch_vccnz .LBB0_1353
	s_add_u32 s6, s44, 0x3a000200
	s_addc_u32 s7, s45, 0
	s_add_u32 s8, s44, 0x3a000400
	s_addc_u32 s9, s45, 0
	s_add_u32 s10, s44, 0x3a000500
	s_addc_u32 s11, s45, 0
	s_add_u32 s12, s44, 0x3a000600
	s_addc_u32 s13, s45, 0
	s_add_u32 s14, s44, 0x3a000700
	s_addc_u32 s15, s45, 0
	s_add_u32 s16, s44, 0x3a000800
	s_addc_u32 s17, s45, 0
	s_add_u32 s18, s44, 0x3a000900
	s_addc_u32 s19, s45, 0
	s_add_u32 s20, s44, 0x3a000a00
	s_addc_u32 s21, s45, 0
	s_add_u32 s22, s44, 0x3a000b00
	s_addc_u32 s23, s45, 0
	s_add_u32 s24, s44, 0x3a000c00
	s_addc_u32 s25, s45, 0
	s_add_u32 s26, s44, 0x3a000d00
	s_addc_u32 s27, s45, 0
	s_add_u32 s28, s44, 0x3a000e00
	s_addc_u32 s29, s45, 0
	s_add_u32 s30, s44, 0x3a000f00
	s_addc_u32 s31, s45, 0
	s_add_u32 s34, s44, 0x3a001000
	s_addc_u32 s35, s45, 0
	s_add_u32 s36, s44, 0x3a001100
	s_addc_u32 s37, s45, 0
	s_add_u32 s38, s44, 0x3a001200
	v_readlane_b32 s3, v244, 0
	s_addc_u32 s39, s45, 0
	s_mul_i32 s3, s47, s3
	s_add_u32 s42, s44, 0x3a001300
	s_mul_i32 s3, s3, s46
	s_addc_u32 s43, s45, 0
	s_mov_b32 s40, 1
	v_mov_b32_e32 v16, 0
	s_branch .LBB0_1341
